# adds P1 epilogue store coalescing via ds_bpermute and straight-line 8-deep prefetched mini GEMM tiles on top of v010
# baseline (speedup 1.0000x reference)
; DEVI unsigned pk_bf16(float lo, float hi) { const f32x2_t v = {lo, hi}; const bf16x2_t b = __builtin_convertvector(v, bf16x2_t); return __builtin_bit_cast(unsigned, b); }
;     DEVI bool next(int i, pg8::Unit& u) const {
;         const int T = 132 * 27;
;         int idx;
;         if (x >= 0) { const int s0 = (x * T) >> 3, s1 = ((x + 1) * T) >> 3; idx = s0 + i * nloc + j; if (idx >= s1) return false; }
;         else { idx = j + i * G; if (idx >= T) return false; }
;     DEVI void operator()(const f32x4 (&acc)[2][2][4][2], const pg8::Unit& u, int wr, int wc, int l15, int g) const {
;     ...
;                 float* fp = fdst + (size_t)(prompt ? tok : tok - NTP) * fw + colo + 4 * g;
; #pragma unroll
;                 for (int nt = 0; nt < 4; ++nt) *(f32x4*)(fp + 16 * nt) = v[nt];
;             }
;             if (wb) {
;                 bf16_t* bp = bdst + (size_t)tok * bw + colo + 16 * (g & 1) + 8 * (g >> 1);
; #pragma unroll
;                 for (int pr = 0; pr < 2; ++pr) {
;                     const unsigned x0 = pk_bf16(v[2 * pr][0], v[2 * pr][1]), x1 = pk_bf16(v[2 * pr][2], v[2 * pr][3]);
;                     const unsigned y0 = pk_bf16(v[2 * pr + 1][0], v[2 * pr + 1][1]), y1 = pk_bf16(v[2 * pr + 1][2], v[2 * pr + 1][3]);
;                     const auto r0 = __builtin_amdgcn_permlane16_swap(x0, y0, false, false);
;                     const auto r1 = __builtin_amdgcn_permlane16_swap(x1, y1, false, false);
;                     const u32x4 o = (u32x4){r0[0], r1[0], r0[1], r1[1]};
;                     *(u32x4*)(bp + 32 * pr) = o;
.LBB0_142:
	v_and_b32_e32 v238, 63, v203
	v_and_b32_e32 v239, 3, v238
	v_lshrrev_b32_e32 v237, 4, v238
	v_bfe_u32 v236, v238, 2, 2
	v_lshl_add_u32 v237, v237, 2, v236
	v_lshl_add_u32 v238, v239, 4, v237
	v_lshlrev_b32_e32 v238, 2, v238
	v_and_b32_e32 v236, 1, v239
	v_lshrrev_b32_e32 v239, 1, v239
	v_lshl_or_b32 v239, v236, 1, v239
	v_lshl_add_u32 v239, v239, 4, v237
	v_lshlrev_b32_e32 v239, 2, v239
	s_and_b32 s0, s97, 7
	s_cmp_lg_u32 s0, 0
	s_cselect_b64 s[78:79], -1, 0
	v_mov_b32_e32 v12, v203
	s_and_b64 vcc, exec, s[78:79]
	v_readfirstlane_b32 s2, v12
	s_cbranch_vccz .LBB0_144
	s_cmpk_lt_i32 s96, 0xdec
	s_mov_b64 s[4:5], 0
	s_cselect_b64 s[0:1], -1, 0
	s_branch .LBB0_145

; DEVI unsigned pk_bf16(float lo, float hi) { const f32x2_t v = {lo, hi}; const bf16x2_t b = __builtin_convertvector(v, bf16x2_t); return __builtin_bit_cast(unsigned, b); }
;     DEVI void operator()(const f32x4 (&acc)[2][2][4][2], const pg8::Unit& u, int wr, int wc, int l15, int g) const {
;     ...
;             if (fdst) {
;                 float* fp = fdst + (size_t)(prompt ? tok : tok - NTP) * fw + colo + 4 * g;
; #pragma unroll
;                 for (int nt = 0; nt < 4; ++nt) *(f32x4*)(fp + 16 * nt) = v[nt];
;             }
;             if (wb) {
;                 bf16_t* bp = bdst + (size_t)tok * bw + colo + 16 * (g & 1) + 8 * (g >> 1);
; #pragma unroll
;                 for (int pr = 0; pr < 2; ++pr) {
;                     const unsigned x0 = pk_bf16(v[2 * pr][0], v[2 * pr][1]), x1 = pk_bf16(v[2 * pr][2], v[2 * pr][3]);
;                     const unsigned y0 = pk_bf16(v[2 * pr + 1][0], v[2 * pr + 1][1]), y1 = pk_bf16(v[2 * pr + 1][2], v[2 * pr + 1][3]);
;                     const auto r0 = __builtin_amdgcn_permlane16_swap(x0, y0, false, false);
;                     const auto r1 = __builtin_amdgcn_permlane16_swap(x1, y1, false, false);
;                     const u32x4 o = (u32x4){r0[0], r1[0], r0[1], r1[1]};
;                     *(u32x4*)(bp + 32 * pr) = o;
;                 }
.LBB0_228:
	s_cmp_lg_u64 s[68:69], 0
	s_cselect_b64 s[70:71], -1, 0
	s_ashr_i32 s13, s12, 31
	s_lshl_b64 s[90:91], s[12:13], 2
	s_add_u32 s90, s68, s90
	s_addc_u32 s91, s69, s91
	s_cmp_eq_u64 s[68:69], 0
	v_lshl_add_u64 v[220:221], s[90:91], 0, v[200:201]
	s_cbranch_scc1 .LBB0_230
	v_add_u32_e32 v116, 0xffff8000, v218
	v_cndmask_b32_e64 v116, v116, v218, s[60:61]
	v_ashrrev_i32_e32 v117, 31, v116
	v_mul_lo_u32 v118, s64, v117
	v_mul_lo_u32 v119, s65, v116
	v_mad_u64_u32 v[116:117], s[68:69], s64, v116, 0
	v_add3_u32 v117, v117, v118, v119
	v_lshl_add_u64 v[116:117], v[116:117], 2, v[220:221]
	ds_bpermute_b32 v236, v238, v116
	ds_bpermute_b32 v237, v238, v117
	ds_bpermute_b32 v240, v238, v132
	ds_bpermute_b32 v241, v238, v133
	ds_bpermute_b32 v242, v238, v134
	ds_bpermute_b32 v243, v238, v135
	ds_bpermute_b32 v244, v238, v136
	ds_bpermute_b32 v245, v238, v137
	ds_bpermute_b32 v246, v238, v138
	ds_bpermute_b32 v247, v238, v139
	s_waitcnt lgkmcnt(4)
	global_store_dwordx4 v[236:237], v[240:243], off
	ds_bpermute_b32 v248, v238, v140
	ds_bpermute_b32 v249, v238, v141
	ds_bpermute_b32 v250, v238, v142
	ds_bpermute_b32 v251, v238, v143
	s_waitcnt lgkmcnt(4)
	global_store_dwordx4 v[236:237], v[244:247], off offset:64
	ds_bpermute_b32 v252, v238, v144
	ds_bpermute_b32 v253, v238, v145
	ds_bpermute_b32 v254, v238, v146
	ds_bpermute_b32 v255, v238, v147
	s_waitcnt lgkmcnt(4)
	global_store_dwordx4 v[236:237], v[248:251], off offset:128
	s_waitcnt lgkmcnt(0)
	global_store_dwordx4 v[236:237], v[252:255], off offset:192
.LBB0_230:
	s_cmp_lg_u64 s[14:15], 0
	s_cselect_b64 s[68:69], -1, 0
	s_and_b64 s[16:17], s[68:69], s[16:17]
	s_lshl_b64 s[12:13], s[12:13], 1
	s_add_u32 s12, s14, s12
	s_addc_u32 s13, s15, s13
	v_mov_b32_e32 v215, v201
	v_lshl_add_u64 v[116:117], s[12:13], 0, v[214:215]
	v_mov_b32_e32 v217, v201
	v_cndmask_b32_e64 v118, 0, 1, s[16:17]
	v_cmp_ne_u32_e64 s[12:13], 1, v118
	s_andn2_b64 vcc, exec, s[16:17]
	v_lshl_add_u64 v[222:223], v[116:117], 0, v[216:217]
	s_cbranch_vccnz .LBB0_232
	v_ashrrev_i32_e32 v116, 31, v218
	v_mul_lo_u32 v118, s63, v218
	v_mul_lo_u32 v119, s62, v116
	v_mad_u64_u32 v[116:117], s[14:15], s62, v218, 0
	v_add3_u32 v117, v117, v119, v118
	v_lshl_add_u64 v[120:121], v[116:117], 1, v[222:223]
	v_cvt_pk_bf16_f32 v116, v132, v133
	v_cvt_pk_bf16_f32 v117, v134, v135
	v_cvt_pk_bf16_f32 v118, v136, v137
	v_cvt_pk_bf16_f32 v119, v138, v139
	s_nop 0
	v_permlane16_swap_b32_e32 v116, v118
	v_permlane16_swap_b32_e32 v117, v119
	ds_bpermute_b32 v236, v239, v120
	ds_bpermute_b32 v237, v239, v121
	ds_bpermute_b32 v240, v239, v116
	ds_bpermute_b32 v241, v239, v117
	ds_bpermute_b32 v242, v239, v118
	ds_bpermute_b32 v243, v239, v119
	s_waitcnt lgkmcnt(0)
	global_store_dwordx4 v[236:237], v[240:243], off
	s_nop 1
	v_cvt_pk_bf16_f32 v116, v140, v141
	v_cvt_pk_bf16_f32 v117, v142, v143
	v_cvt_pk_bf16_f32 v118, v144, v145
	v_cvt_pk_bf16_f32 v119, v146, v147
	s_nop 0
	v_permlane16_swap_b32_e32 v116, v118
	v_permlane16_swap_b32_e32 v117, v119
	ds_bpermute_b32 v244, v239, v116
	ds_bpermute_b32 v245, v239, v117
	ds_bpermute_b32 v246, v239, v118
	ds_bpermute_b32 v247, v239, v119
	s_waitcnt lgkmcnt(0)
	global_store_dwordx4 v[236:237], v[244:247], off offset:64

; DEVI unsigned pk_bf16(float lo, float hi) { const f32x2_t v = {lo, hi}; const bf16x2_t b = __builtin_convertvector(v, bf16x2_t); return __builtin_bit_cast(unsigned, b); }
;     DEVI void operator()(const f32x4 (&acc)[2][2][4][2], const pg8::Unit& u, int wr, int wc, int l15, int g) const {
;     ...
;             if (fdst) {
;                 float* fp = fdst + (size_t)(prompt ? tok : tok - NTP) * fw + colo + 4 * g;
; #pragma unroll
;                 for (int nt = 0; nt < 4; ++nt) *(f32x4*)(fp + 16 * nt) = v[nt];
;             }
;             if (wb) {
;                 bf16_t* bp = bdst + (size_t)tok * bw + colo + 16 * (g & 1) + 8 * (g >> 1);
; #pragma unroll
;                 for (int pr = 0; pr < 2; ++pr) {
;                     const unsigned x0 = pk_bf16(v[2 * pr][0], v[2 * pr][1]), x1 = pk_bf16(v[2 * pr][2], v[2 * pr][3]);
;                     const unsigned y0 = pk_bf16(v[2 * pr + 1][0], v[2 * pr + 1][1]), y1 = pk_bf16(v[2 * pr + 1][2], v[2 * pr + 1][3]);
;                     const auto r0 = __builtin_amdgcn_permlane16_swap(x0, y0, false, false);
;                     const auto r1 = __builtin_amdgcn_permlane16_swap(x1, y1, false, false);
;                     const u32x4 o = (u32x4){r0[0], r1[0], r0[1], r1[1]};
;                     *(u32x4*)(bp + 32 * pr) = o;
;                 }
.LBB0_243:
	v_cndmask_b32_e64 v100, 0, 1, s[70:71]
	v_cmp_ne_u32_e64 s[16:17], 1, v100
	s_andn2_b64 vcc, exec, s[70:71]
	v_or_b32_e32 v100, 16, v218
	s_cbranch_vccnz .LBB0_245
	v_add_u32_e32 v101, 0xffff8010, v218
	v_cndmask_b32_e64 v101, v101, v100, s[60:61]
	v_ashrrev_i32_e32 v102, 31, v101
	v_mul_lo_u32 v104, s64, v102
	v_mul_lo_u32 v105, s65, v101
	v_mad_u64_u32 v[102:103], s[68:69], s64, v101, 0
	v_add3_u32 v103, v103, v104, v105
	v_lshl_add_u64 v[102:103], v[102:103], 2, v[220:221]
	ds_bpermute_b32 v236, v238, v102
	ds_bpermute_b32 v237, v238, v103
	ds_bpermute_b32 v240, v238, v132
	ds_bpermute_b32 v241, v238, v133
	ds_bpermute_b32 v242, v238, v134
	ds_bpermute_b32 v243, v238, v135
	ds_bpermute_b32 v244, v238, v136
	ds_bpermute_b32 v245, v238, v137
	ds_bpermute_b32 v246, v238, v138
	ds_bpermute_b32 v247, v238, v139
	s_waitcnt lgkmcnt(4)
	global_store_dwordx4 v[236:237], v[240:243], off
	ds_bpermute_b32 v248, v238, v140
	ds_bpermute_b32 v249, v238, v141
	ds_bpermute_b32 v250, v238, v142
	ds_bpermute_b32 v251, v238, v143
	s_waitcnt lgkmcnt(4)
	global_store_dwordx4 v[236:237], v[244:247], off offset:64
	ds_bpermute_b32 v252, v238, v144
	ds_bpermute_b32 v253, v238, v145
	ds_bpermute_b32 v254, v238, v146
	ds_bpermute_b32 v255, v238, v147
	s_waitcnt lgkmcnt(4)
	global_store_dwordx4 v[236:237], v[248:251], off offset:128
	s_waitcnt lgkmcnt(0)
	global_store_dwordx4 v[236:237], v[252:255], off offset:192
.LBB0_245:
	s_and_b64 vcc, exec, s[12:13]
	s_cbranch_vccnz .LBB0_247
	v_ashrrev_i32_e32 v101, 31, v100
	v_mul_lo_u32 v102, s63, v100
	v_mul_lo_u32 v103, s62, v101
	v_mad_u64_u32 v[100:101], s[68:69], s62, v100, 0
	v_add3_u32 v101, v101, v103, v102
	v_lshl_add_u64 v[104:105], v[100:101], 1, v[222:223]
	v_cvt_pk_bf16_f32 v100, v132, v133
	v_cvt_pk_bf16_f32 v101, v134, v135
	v_cvt_pk_bf16_f32 v102, v136, v137
	v_cvt_pk_bf16_f32 v103, v138, v139
	s_nop 0
	v_permlane16_swap_b32_e32 v100, v102
	v_permlane16_swap_b32_e32 v101, v103
	ds_bpermute_b32 v236, v239, v104
	ds_bpermute_b32 v237, v239, v105
	ds_bpermute_b32 v240, v239, v100
	ds_bpermute_b32 v241, v239, v101
	ds_bpermute_b32 v242, v239, v102
	ds_bpermute_b32 v243, v239, v103
	s_waitcnt lgkmcnt(0)
	global_store_dwordx4 v[236:237], v[240:243], off
	s_nop 1
	v_cvt_pk_bf16_f32 v100, v140, v141
	v_cvt_pk_bf16_f32 v101, v142, v143
	v_cvt_pk_bf16_f32 v102, v144, v145
	v_cvt_pk_bf16_f32 v103, v146, v147
	s_nop 0
	v_permlane16_swap_b32_e32 v100, v102
	v_permlane16_swap_b32_e32 v101, v103
	ds_bpermute_b32 v244, v239, v100
	ds_bpermute_b32 v245, v239, v101
	ds_bpermute_b32 v246, v239, v102
	ds_bpermute_b32 v247, v239, v103
	s_waitcnt lgkmcnt(0)
	global_store_dwordx4 v[236:237], v[244:247], off offset:64

; DEVI unsigned pk_bf16(float lo, float hi) { const f32x2_t v = {lo, hi}; const bf16x2_t b = __builtin_convertvector(v, bf16x2_t); return __builtin_bit_cast(unsigned, b); }
;     DEVI void operator()(const f32x4 (&acc)[2][2][4][2], const pg8::Unit& u, int wr, int wc, int l15, int g) const {
;     ...
;             if (fdst) {
;                 float* fp = fdst + (size_t)(prompt ? tok : tok - NTP) * fw + colo + 4 * g;
; #pragma unroll
;                 for (int nt = 0; nt < 4; ++nt) *(f32x4*)(fp + 16 * nt) = v[nt];
;             }
;             if (wb) {
;                 bf16_t* bp = bdst + (size_t)tok * bw + colo + 16 * (g & 1) + 8 * (g >> 1);
; #pragma unroll
;                 for (int pr = 0; pr < 2; ++pr) {
;                     const unsigned x0 = pk_bf16(v[2 * pr][0], v[2 * pr][1]), x1 = pk_bf16(v[2 * pr][2], v[2 * pr][3]);
;                     const unsigned y0 = pk_bf16(v[2 * pr + 1][0], v[2 * pr + 1][1]), y1 = pk_bf16(v[2 * pr + 1][2], v[2 * pr + 1][3]);
;                     const auto r0 = __builtin_amdgcn_permlane16_swap(x0, y0, false, false);
;                     const auto r1 = __builtin_amdgcn_permlane16_swap(x1, y1, false, false);
;                     const u32x4 o = (u32x4){r0[0], r1[0], r0[1], r1[1]};
;                     *(u32x4*)(bp + 32 * pr) = o;
;                 }
.LBB0_259:
	v_add_u32_e32 v85, 0xffff8020, v218
	v_cndmask_b32_e64 v85, v85, v84, s[60:61]
	v_ashrrev_i32_e32 v86, 31, v85
	v_mul_lo_u32 v88, s64, v86
	v_mul_lo_u32 v89, s65, v85
	v_mad_u64_u32 v[86:87], s[68:69], s64, v85, 0
	v_add3_u32 v87, v87, v88, v89
	v_lshl_add_u64 v[86:87], v[86:87], 2, v[220:221]
	ds_bpermute_b32 v236, v238, v86
	ds_bpermute_b32 v237, v238, v87
	ds_bpermute_b32 v240, v238, v132
	ds_bpermute_b32 v241, v238, v133
	ds_bpermute_b32 v242, v238, v134
	ds_bpermute_b32 v243, v238, v135
	ds_bpermute_b32 v244, v238, v136
	ds_bpermute_b32 v245, v238, v137
	ds_bpermute_b32 v246, v238, v138
	ds_bpermute_b32 v247, v238, v139
	s_waitcnt lgkmcnt(4)
	global_store_dwordx4 v[236:237], v[240:243], off
	ds_bpermute_b32 v248, v238, v140
	ds_bpermute_b32 v249, v238, v141
	ds_bpermute_b32 v250, v238, v142
	ds_bpermute_b32 v251, v238, v143
	s_waitcnt lgkmcnt(4)
	global_store_dwordx4 v[236:237], v[244:247], off offset:64
	ds_bpermute_b32 v252, v238, v144
	ds_bpermute_b32 v253, v238, v145
	ds_bpermute_b32 v254, v238, v146
	ds_bpermute_b32 v255, v238, v147
	s_waitcnt lgkmcnt(4)
	global_store_dwordx4 v[236:237], v[248:251], off offset:128
	s_waitcnt lgkmcnt(0)
	global_store_dwordx4 v[236:237], v[252:255], off offset:192
.LBB0_260:
	s_and_b64 vcc, exec, s[12:13]
	s_cbranch_vccnz .LBB0_262
	v_ashrrev_i32_e32 v85, 31, v84
	v_mul_lo_u32 v86, s63, v84
	v_mul_lo_u32 v87, s62, v85
	v_mad_u64_u32 v[84:85], s[68:69], s62, v84, 0
	v_add3_u32 v85, v85, v87, v86
	v_lshl_add_u64 v[88:89], v[84:85], 1, v[222:223]
	v_cvt_pk_bf16_f32 v84, v132, v133
	v_cvt_pk_bf16_f32 v85, v134, v135
	v_cvt_pk_bf16_f32 v86, v136, v137
	v_cvt_pk_bf16_f32 v87, v138, v139
	s_nop 0
	v_permlane16_swap_b32_e32 v84, v86
	v_permlane16_swap_b32_e32 v85, v87
	ds_bpermute_b32 v236, v239, v88
	ds_bpermute_b32 v237, v239, v89
	ds_bpermute_b32 v240, v239, v84
	ds_bpermute_b32 v241, v239, v85
	ds_bpermute_b32 v242, v239, v86
	ds_bpermute_b32 v243, v239, v87
	s_waitcnt lgkmcnt(0)
	global_store_dwordx4 v[236:237], v[240:243], off
	s_nop 1
	v_cvt_pk_bf16_f32 v84, v140, v141
	v_cvt_pk_bf16_f32 v85, v142, v143
	v_cvt_pk_bf16_f32 v86, v144, v145
	v_cvt_pk_bf16_f32 v87, v146, v147
	s_nop 0
	v_permlane16_swap_b32_e32 v84, v86
	v_permlane16_swap_b32_e32 v85, v87
	ds_bpermute_b32 v244, v239, v84
	ds_bpermute_b32 v245, v239, v85
	ds_bpermute_b32 v246, v239, v86
	ds_bpermute_b32 v247, v239, v87
	s_waitcnt lgkmcnt(0)
	global_store_dwordx4 v[236:237], v[244:247], off offset:64

; DEVI unsigned pk_bf16(float lo, float hi) { const f32x2_t v = {lo, hi}; const bf16x2_t b = __builtin_convertvector(v, bf16x2_t); return __builtin_bit_cast(unsigned, b); }
;     DEVI void operator()(const f32x4 (&acc)[2][2][4][2], const pg8::Unit& u, int wr, int wc, int l15, int g) const {
;     ...
;             if (fdst) {
;                 float* fp = fdst + (size_t)(prompt ? tok : tok - NTP) * fw + colo + 4 * g;
; #pragma unroll
;                 for (int nt = 0; nt < 4; ++nt) *(f32x4*)(fp + 16 * nt) = v[nt];
;             }
;             if (wb) {
;                 bf16_t* bp = bdst + (size_t)tok * bw + colo + 16 * (g & 1) + 8 * (g >> 1);
; #pragma unroll
;                 for (int pr = 0; pr < 2; ++pr) {
;                     const unsigned x0 = pk_bf16(v[2 * pr][0], v[2 * pr][1]), x1 = pk_bf16(v[2 * pr][2], v[2 * pr][3]);
;                     const unsigned y0 = pk_bf16(v[2 * pr + 1][0], v[2 * pr + 1][1]), y1 = pk_bf16(v[2 * pr + 1][2], v[2 * pr + 1][3]);
;                     const auto r0 = __builtin_amdgcn_permlane16_swap(x0, y0, false, false);
;                     const auto r1 = __builtin_amdgcn_permlane16_swap(x1, y1, false, false);
;                     const u32x4 o = (u32x4){r0[0], r1[0], r0[1], r1[1]};
;                     *(u32x4*)(bp + 32 * pr) = o;
;                 }
.LBB0_274:
	v_add_u32_e32 v69, 0xffff8030, v218
	v_cndmask_b32_e64 v69, v69, v68, s[60:61]
	v_ashrrev_i32_e32 v70, 31, v69
	v_mul_lo_u32 v72, s64, v70
	v_mul_lo_u32 v73, s65, v69
	v_mad_u64_u32 v[70:71], s[68:69], s64, v69, 0
	v_add3_u32 v71, v71, v72, v73
	v_lshl_add_u64 v[70:71], v[70:71], 2, v[220:221]
	ds_bpermute_b32 v236, v238, v70
	ds_bpermute_b32 v237, v238, v71
	ds_bpermute_b32 v240, v238, v132
	ds_bpermute_b32 v241, v238, v133
	ds_bpermute_b32 v242, v238, v134
	ds_bpermute_b32 v243, v238, v135
	ds_bpermute_b32 v244, v238, v136
	ds_bpermute_b32 v245, v238, v137
	ds_bpermute_b32 v246, v238, v138
	ds_bpermute_b32 v247, v238, v139
	s_waitcnt lgkmcnt(4)
	global_store_dwordx4 v[236:237], v[240:243], off
	ds_bpermute_b32 v248, v238, v140
	ds_bpermute_b32 v249, v238, v141
	ds_bpermute_b32 v250, v238, v142
	ds_bpermute_b32 v251, v238, v143
	s_waitcnt lgkmcnt(4)
	global_store_dwordx4 v[236:237], v[244:247], off offset:64
	ds_bpermute_b32 v252, v238, v144
	ds_bpermute_b32 v253, v238, v145
	ds_bpermute_b32 v254, v238, v146
	ds_bpermute_b32 v255, v238, v147
	s_waitcnt lgkmcnt(4)
	global_store_dwordx4 v[236:237], v[248:251], off offset:128
	s_waitcnt lgkmcnt(0)
	global_store_dwordx4 v[236:237], v[252:255], off offset:192
.LBB0_275:
	s_and_b64 vcc, exec, s[12:13]
	s_cbranch_vccnz .LBB0_277
	v_ashrrev_i32_e32 v69, 31, v68
	v_mul_lo_u32 v70, s63, v68
	v_mul_lo_u32 v71, s62, v69
	v_mad_u64_u32 v[68:69], s[68:69], s62, v68, 0
	v_add3_u32 v69, v69, v71, v70
	v_lshl_add_u64 v[72:73], v[68:69], 1, v[222:223]
	v_cvt_pk_bf16_f32 v68, v132, v133
	v_cvt_pk_bf16_f32 v69, v134, v135
	v_cvt_pk_bf16_f32 v70, v136, v137
	v_cvt_pk_bf16_f32 v71, v138, v139
	s_nop 0
	v_permlane16_swap_b32_e32 v68, v70
	v_permlane16_swap_b32_e32 v69, v71
	ds_bpermute_b32 v236, v239, v72
	ds_bpermute_b32 v237, v239, v73
	ds_bpermute_b32 v240, v239, v68
	ds_bpermute_b32 v241, v239, v69
	ds_bpermute_b32 v242, v239, v70
	ds_bpermute_b32 v243, v239, v71
	s_waitcnt lgkmcnt(0)
	global_store_dwordx4 v[236:237], v[240:243], off
	s_nop 1
	v_cvt_pk_bf16_f32 v68, v140, v141
	v_cvt_pk_bf16_f32 v69, v142, v143
	v_cvt_pk_bf16_f32 v70, v144, v145
	v_cvt_pk_bf16_f32 v71, v146, v147
	s_nop 0
	v_permlane16_swap_b32_e32 v68, v70
	v_permlane16_swap_b32_e32 v69, v71
	ds_bpermute_b32 v244, v239, v68
	ds_bpermute_b32 v245, v239, v69
	ds_bpermute_b32 v246, v239, v70
	ds_bpermute_b32 v247, v239, v71
	s_waitcnt lgkmcnt(0)
	global_store_dwordx4 v[236:237], v[244:247], off offset:64

; DEVI unsigned pk_bf16(float lo, float hi) { const f32x2_t v = {lo, hi}; const bf16x2_t b = __builtin_convertvector(v, bf16x2_t); return __builtin_bit_cast(unsigned, b); }
;     DEVI void operator()(const f32x4 (&acc)[2][2][4][2], const pg8::Unit& u, int wr, int wc, int l15, int g) const {
;     ...
;             if (fdst) {
;                 float* fp = fdst + (size_t)(prompt ? tok : tok - NTP) * fw + colo + 4 * g;
; #pragma unroll
;                 for (int nt = 0; nt < 4; ++nt) *(f32x4*)(fp + 16 * nt) = v[nt];
;             }
;             if (wb) {
;                 bf16_t* bp = bdst + (size_t)tok * bw + colo + 16 * (g & 1) + 8 * (g >> 1);
; #pragma unroll
;                 for (int pr = 0; pr < 2; ++pr) {
;                     const unsigned x0 = pk_bf16(v[2 * pr][0], v[2 * pr][1]), x1 = pk_bf16(v[2 * pr][2], v[2 * pr][3]);
;                     const unsigned y0 = pk_bf16(v[2 * pr + 1][0], v[2 * pr + 1][1]), y1 = pk_bf16(v[2 * pr + 1][2], v[2 * pr + 1][3]);
;                     const auto r0 = __builtin_amdgcn_permlane16_swap(x0, y0, false, false);
;                     const auto r1 = __builtin_amdgcn_permlane16_swap(x1, y1, false, false);
;                     const u32x4 o = (u32x4){r0[0], r1[0], r0[1], r1[1]};
;                     *(u32x4*)(bp + 32 * pr) = o;
;                 }
.LBB0_291:
	v_add_u32_e32 v52, 0xffff8080, v218
	v_cndmask_b32_e64 v52, v52, v71, s[60:61]
	v_ashrrev_i32_e32 v53, 31, v52
	v_mul_lo_u32 v54, s64, v53
	v_mul_lo_u32 v55, s65, v52
	v_mad_u64_u32 v[52:53], s[68:69], s64, v52, 0
	v_add3_u32 v53, v53, v54, v55
	v_lshl_add_u64 v[52:53], v[52:53], 2, v[220:221]
	ds_bpermute_b32 v236, v238, v52
	ds_bpermute_b32 v237, v238, v53
	ds_bpermute_b32 v240, v238, v132
	ds_bpermute_b32 v241, v238, v133
	ds_bpermute_b32 v242, v238, v134
	ds_bpermute_b32 v243, v238, v135
	ds_bpermute_b32 v244, v238, v136
	ds_bpermute_b32 v245, v238, v137
	ds_bpermute_b32 v246, v238, v138
	ds_bpermute_b32 v247, v238, v139
	s_waitcnt lgkmcnt(4)
	global_store_dwordx4 v[236:237], v[240:243], off
	ds_bpermute_b32 v248, v238, v140
	ds_bpermute_b32 v249, v238, v141
	ds_bpermute_b32 v250, v238, v142
	ds_bpermute_b32 v251, v238, v143
	s_waitcnt lgkmcnt(4)
	global_store_dwordx4 v[236:237], v[244:247], off offset:64
	ds_bpermute_b32 v252, v238, v144
	ds_bpermute_b32 v253, v238, v145
	ds_bpermute_b32 v254, v238, v146
	ds_bpermute_b32 v255, v238, v147
	s_waitcnt lgkmcnt(4)
	global_store_dwordx4 v[236:237], v[248:251], off offset:128
	s_waitcnt lgkmcnt(0)
	global_store_dwordx4 v[236:237], v[252:255], off offset:192
.LBB0_292:
	s_and_b64 vcc, exec, s[12:13]
	s_cbranch_vccnz .LBB0_294
	v_ashrrev_i32_e32 v52, 31, v71
	v_mul_lo_u32 v54, s63, v71
	v_mul_lo_u32 v55, s62, v52
	v_mad_u64_u32 v[52:53], s[68:69], s62, v71, 0
	v_add3_u32 v53, v53, v55, v54
	v_lshl_add_u64 v[56:57], v[52:53], 1, v[222:223]
	v_cvt_pk_bf16_f32 v52, v132, v133
	v_cvt_pk_bf16_f32 v53, v134, v135
	v_cvt_pk_bf16_f32 v54, v136, v137
	v_cvt_pk_bf16_f32 v55, v138, v139
	s_nop 0
	v_permlane16_swap_b32_e32 v52, v54
	v_permlane16_swap_b32_e32 v53, v55
	ds_bpermute_b32 v236, v239, v56
	ds_bpermute_b32 v237, v239, v57
	ds_bpermute_b32 v240, v239, v52
	ds_bpermute_b32 v241, v239, v53
	ds_bpermute_b32 v242, v239, v54
	ds_bpermute_b32 v243, v239, v55
	s_waitcnt lgkmcnt(0)
	global_store_dwordx4 v[236:237], v[240:243], off
	s_nop 1
	v_cvt_pk_bf16_f32 v52, v140, v141
	v_cvt_pk_bf16_f32 v53, v142, v143
	v_cvt_pk_bf16_f32 v54, v144, v145
	v_cvt_pk_bf16_f32 v55, v146, v147
	s_nop 0
	v_permlane16_swap_b32_e32 v52, v54
	v_permlane16_swap_b32_e32 v53, v55
	ds_bpermute_b32 v244, v239, v52
	ds_bpermute_b32 v245, v239, v53
	ds_bpermute_b32 v246, v239, v54
	ds_bpermute_b32 v247, v239, v55
	s_waitcnt lgkmcnt(0)
	global_store_dwordx4 v[236:237], v[244:247], off offset:64

; DEVI unsigned pk_bf16(float lo, float hi) { const f32x2_t v = {lo, hi}; const bf16x2_t b = __builtin_convertvector(v, bf16x2_t); return __builtin_bit_cast(unsigned, b); }
;     DEVI void operator()(const f32x4 (&acc)[2][2][4][2], const pg8::Unit& u, int wr, int wc, int l15, int g) const {
;     ...
;             if (fdst) {
;                 float* fp = fdst + (size_t)(prompt ? tok : tok - NTP) * fw + colo + 4 * g;
; #pragma unroll
;                 for (int nt = 0; nt < 4; ++nt) *(f32x4*)(fp + 16 * nt) = v[nt];
;             }
;             if (wb) {
;                 bf16_t* bp = bdst + (size_t)tok * bw + colo + 16 * (g & 1) + 8 * (g >> 1);
; #pragma unroll
;                 for (int pr = 0; pr < 2; ++pr) {
;                     const unsigned x0 = pk_bf16(v[2 * pr][0], v[2 * pr][1]), x1 = pk_bf16(v[2 * pr][2], v[2 * pr][3]);
;                     const unsigned y0 = pk_bf16(v[2 * pr + 1][0], v[2 * pr + 1][1]), y1 = pk_bf16(v[2 * pr + 1][2], v[2 * pr + 1][3]);
;                     const auto r0 = __builtin_amdgcn_permlane16_swap(x0, y0, false, false);
;                     const auto r1 = __builtin_amdgcn_permlane16_swap(x1, y1, false, false);
;                     const u32x4 o = (u32x4){r0[0], r1[0], r0[1], r1[1]};
;                     *(u32x4*)(bp + 32 * pr) = o;
;                 }
.LBB0_306:
	v_add_u32_e32 v36, 0xffff8090, v218
	v_cndmask_b32_e64 v36, v36, v70, s[60:61]
	v_ashrrev_i32_e32 v37, 31, v36
	v_mul_lo_u32 v38, s64, v37
	v_mul_lo_u32 v39, s65, v36
	v_mad_u64_u32 v[36:37], s[68:69], s64, v36, 0
	v_add3_u32 v37, v37, v38, v39
	v_lshl_add_u64 v[36:37], v[36:37], 2, v[220:221]
	ds_bpermute_b32 v236, v238, v36
	ds_bpermute_b32 v237, v238, v37
	ds_bpermute_b32 v240, v238, v132
	ds_bpermute_b32 v241, v238, v133
	ds_bpermute_b32 v242, v238, v134
	ds_bpermute_b32 v243, v238, v135
	ds_bpermute_b32 v244, v238, v136
	ds_bpermute_b32 v245, v238, v137
	ds_bpermute_b32 v246, v238, v138
	ds_bpermute_b32 v247, v238, v139
	s_waitcnt lgkmcnt(4)
	global_store_dwordx4 v[236:237], v[240:243], off
	ds_bpermute_b32 v248, v238, v140
	ds_bpermute_b32 v249, v238, v141
	ds_bpermute_b32 v250, v238, v142
	ds_bpermute_b32 v251, v238, v143
	s_waitcnt lgkmcnt(4)
	global_store_dwordx4 v[236:237], v[244:247], off offset:64
	ds_bpermute_b32 v252, v238, v144
	ds_bpermute_b32 v253, v238, v145
	ds_bpermute_b32 v254, v238, v146
	ds_bpermute_b32 v255, v238, v147
	s_waitcnt lgkmcnt(4)
	global_store_dwordx4 v[236:237], v[248:251], off offset:128
	s_waitcnt lgkmcnt(0)
	global_store_dwordx4 v[236:237], v[252:255], off offset:192
.LBB0_307:
	s_and_b64 vcc, exec, s[12:13]
	s_cbranch_vccnz .LBB0_309
	v_ashrrev_i32_e32 v36, 31, v70
	v_mul_lo_u32 v38, s63, v70
	v_mul_lo_u32 v39, s62, v36
	v_mad_u64_u32 v[36:37], s[68:69], s62, v70, 0
	v_add3_u32 v37, v37, v39, v38
	v_lshl_add_u64 v[40:41], v[36:37], 1, v[222:223]
	v_cvt_pk_bf16_f32 v36, v132, v133
	v_cvt_pk_bf16_f32 v37, v134, v135
	v_cvt_pk_bf16_f32 v38, v136, v137
	v_cvt_pk_bf16_f32 v39, v138, v139
	s_nop 0
	v_permlane16_swap_b32_e32 v36, v38
	v_permlane16_swap_b32_e32 v37, v39
	ds_bpermute_b32 v236, v239, v40
	ds_bpermute_b32 v237, v239, v41
	ds_bpermute_b32 v240, v239, v36
	ds_bpermute_b32 v241, v239, v37
	ds_bpermute_b32 v242, v239, v38
	ds_bpermute_b32 v243, v239, v39
	s_waitcnt lgkmcnt(0)
	global_store_dwordx4 v[236:237], v[240:243], off
	s_nop 1
	v_cvt_pk_bf16_f32 v36, v140, v141
	v_cvt_pk_bf16_f32 v37, v142, v143
	v_cvt_pk_bf16_f32 v38, v144, v145
	v_cvt_pk_bf16_f32 v39, v146, v147
	s_nop 0
	v_permlane16_swap_b32_e32 v36, v38
	v_permlane16_swap_b32_e32 v37, v39
	ds_bpermute_b32 v244, v239, v36
	ds_bpermute_b32 v245, v239, v37
	ds_bpermute_b32 v246, v239, v38
	ds_bpermute_b32 v247, v239, v39
	s_waitcnt lgkmcnt(0)
	global_store_dwordx4 v[236:237], v[244:247], off offset:64

; DEVI unsigned pk_bf16(float lo, float hi) { const f32x2_t v = {lo, hi}; const bf16x2_t b = __builtin_convertvector(v, bf16x2_t); return __builtin_bit_cast(unsigned, b); }
;     DEVI void operator()(const f32x4 (&acc)[2][2][4][2], const pg8::Unit& u, int wr, int wc, int l15, int g) const {
;     ...
;             if (fdst) {
;                 float* fp = fdst + (size_t)(prompt ? tok : tok - NTP) * fw + colo + 4 * g;
; #pragma unroll
;                 for (int nt = 0; nt < 4; ++nt) *(f32x4*)(fp + 16 * nt) = v[nt];
;             }
;             if (wb) {
;                 bf16_t* bp = bdst + (size_t)tok * bw + colo + 16 * (g & 1) + 8 * (g >> 1);
; #pragma unroll
;                 for (int pr = 0; pr < 2; ++pr) {
;                     const unsigned x0 = pk_bf16(v[2 * pr][0], v[2 * pr][1]), x1 = pk_bf16(v[2 * pr][2], v[2 * pr][3]);
;                     const unsigned y0 = pk_bf16(v[2 * pr + 1][0], v[2 * pr + 1][1]), y1 = pk_bf16(v[2 * pr + 1][2], v[2 * pr + 1][3]);
;                     const auto r0 = __builtin_amdgcn_permlane16_swap(x0, y0, false, false);
;                     const auto r1 = __builtin_amdgcn_permlane16_swap(x1, y1, false, false);
;                     const u32x4 o = (u32x4){r0[0], r1[0], r0[1], r1[1]};
;                     *(u32x4*)(bp + 32 * pr) = o;
;                 }
.LBB0_321:
	v_add_u32_e32 v20, 0xffff80a0, v218
	v_cndmask_b32_e64 v20, v20, v69, s[60:61]
	v_ashrrev_i32_e32 v21, 31, v20
	v_mul_lo_u32 v22, s64, v21
	v_mul_lo_u32 v23, s65, v20
	v_mad_u64_u32 v[20:21], s[68:69], s64, v20, 0
	v_add3_u32 v21, v21, v22, v23
	v_lshl_add_u64 v[20:21], v[20:21], 2, v[220:221]
	ds_bpermute_b32 v236, v238, v20
	ds_bpermute_b32 v237, v238, v21
	ds_bpermute_b32 v240, v238, v132
	ds_bpermute_b32 v241, v238, v133
	ds_bpermute_b32 v242, v238, v134
	ds_bpermute_b32 v243, v238, v135
	ds_bpermute_b32 v244, v238, v136
	ds_bpermute_b32 v245, v238, v137
	ds_bpermute_b32 v246, v238, v138
	ds_bpermute_b32 v247, v238, v139
	s_waitcnt lgkmcnt(4)
	global_store_dwordx4 v[236:237], v[240:243], off
	ds_bpermute_b32 v248, v238, v140
	ds_bpermute_b32 v249, v238, v141
	ds_bpermute_b32 v250, v238, v142
	ds_bpermute_b32 v251, v238, v143
	s_waitcnt lgkmcnt(4)
	global_store_dwordx4 v[236:237], v[244:247], off offset:64
	ds_bpermute_b32 v252, v238, v144
	ds_bpermute_b32 v253, v238, v145
	ds_bpermute_b32 v254, v238, v146
	ds_bpermute_b32 v255, v238, v147
	s_waitcnt lgkmcnt(4)
	global_store_dwordx4 v[236:237], v[248:251], off offset:128
	s_waitcnt lgkmcnt(0)
	global_store_dwordx4 v[236:237], v[252:255], off offset:192
.LBB0_322:
	s_and_b64 vcc, exec, s[12:13]
	s_cbranch_vccnz .LBB0_324
	v_ashrrev_i32_e32 v20, 31, v69
	v_mul_lo_u32 v22, s63, v69
	v_mul_lo_u32 v23, s62, v20
	v_mad_u64_u32 v[20:21], s[68:69], s62, v69, 0
	v_add3_u32 v21, v21, v23, v22
	v_lshl_add_u64 v[24:25], v[20:21], 1, v[222:223]
	v_cvt_pk_bf16_f32 v20, v132, v133
	v_cvt_pk_bf16_f32 v21, v134, v135
	v_cvt_pk_bf16_f32 v22, v136, v137
	v_cvt_pk_bf16_f32 v23, v138, v139
	s_nop 0
	v_permlane16_swap_b32_e32 v20, v22
	v_permlane16_swap_b32_e32 v21, v23
	ds_bpermute_b32 v236, v239, v24
	ds_bpermute_b32 v237, v239, v25
	ds_bpermute_b32 v240, v239, v20
	ds_bpermute_b32 v241, v239, v21
	ds_bpermute_b32 v242, v239, v22
	ds_bpermute_b32 v243, v239, v23
	s_waitcnt lgkmcnt(0)
	global_store_dwordx4 v[236:237], v[240:243], off
	s_nop 1
	v_cvt_pk_bf16_f32 v20, v140, v141
	v_cvt_pk_bf16_f32 v21, v142, v143
	v_cvt_pk_bf16_f32 v22, v144, v145
	v_cvt_pk_bf16_f32 v23, v146, v147
	s_nop 0
	v_permlane16_swap_b32_e32 v20, v22
	v_permlane16_swap_b32_e32 v21, v23
	ds_bpermute_b32 v244, v239, v20
	ds_bpermute_b32 v245, v239, v21
	ds_bpermute_b32 v246, v239, v22
	ds_bpermute_b32 v247, v239, v23
	s_waitcnt lgkmcnt(0)
	global_store_dwordx4 v[236:237], v[244:247], off offset:64

; DEVI unsigned pk_bf16(float lo, float hi) { const f32x2_t v = {lo, hi}; const bf16x2_t b = __builtin_convertvector(v, bf16x2_t); return __builtin_bit_cast(unsigned, b); }
;     DEVI void operator()(const f32x4 (&acc)[2][2][4][2], const pg8::Unit& u, int wr, int wc, int l15, int g) const {
;     ...
;             if (fdst) {
;                 float* fp = fdst + (size_t)(prompt ? tok : tok - NTP) * fw + colo + 4 * g;
; #pragma unroll
;                 for (int nt = 0; nt < 4; ++nt) *(f32x4*)(fp + 16 * nt) = v[nt];
;             }
;             if (wb) {
;                 bf16_t* bp = bdst + (size_t)tok * bw + colo + 16 * (g & 1) + 8 * (g >> 1);
; #pragma unroll
;                 for (int pr = 0; pr < 2; ++pr) {
;                     const unsigned x0 = pk_bf16(v[2 * pr][0], v[2 * pr][1]), x1 = pk_bf16(v[2 * pr][2], v[2 * pr][3]);
;                     const unsigned y0 = pk_bf16(v[2 * pr + 1][0], v[2 * pr + 1][1]), y1 = pk_bf16(v[2 * pr + 1][2], v[2 * pr + 1][3]);
;                     const auto r0 = __builtin_amdgcn_permlane16_swap(x0, y0, false, false);
;                     const auto r1 = __builtin_amdgcn_permlane16_swap(x1, y1, false, false);
;                     const u32x4 o = (u32x4){r0[0], r1[0], r0[1], r1[1]};
;                     *(u32x4*)(bp + 32 * pr) = o;
;                 }
.LBB0_336:
	v_add_u32_e32 v4, 0xffff80b0, v218
	v_cndmask_b32_e64 v4, v4, v68, s[60:61]
	v_ashrrev_i32_e32 v5, 31, v4
	v_mul_lo_u32 v6, s64, v5
	v_mul_lo_u32 v7, s65, v4
	v_mad_u64_u32 v[4:5], s[4:5], s64, v4, 0
	v_add3_u32 v5, v5, v6, v7
	v_lshl_add_u64 v[4:5], v[4:5], 2, v[220:221]
	ds_bpermute_b32 v236, v238, v4
	ds_bpermute_b32 v237, v238, v5
	ds_bpermute_b32 v240, v238, v132
	ds_bpermute_b32 v241, v238, v133
	ds_bpermute_b32 v242, v238, v134
	ds_bpermute_b32 v243, v238, v135
	ds_bpermute_b32 v244, v238, v136
	ds_bpermute_b32 v245, v238, v137
	ds_bpermute_b32 v246, v238, v138
	ds_bpermute_b32 v247, v238, v139
	s_waitcnt lgkmcnt(4)
	global_store_dwordx4 v[236:237], v[240:243], off
	ds_bpermute_b32 v248, v238, v140
	ds_bpermute_b32 v249, v238, v141
	ds_bpermute_b32 v250, v238, v142
	ds_bpermute_b32 v251, v238, v143
	s_waitcnt lgkmcnt(4)
	global_store_dwordx4 v[236:237], v[244:247], off offset:64
	ds_bpermute_b32 v252, v238, v144
	ds_bpermute_b32 v253, v238, v145
	ds_bpermute_b32 v254, v238, v146
	ds_bpermute_b32 v255, v238, v147
	s_waitcnt lgkmcnt(4)
	global_store_dwordx4 v[236:237], v[248:251], off offset:128
	s_waitcnt lgkmcnt(0)
	global_store_dwordx4 v[236:237], v[252:255], off offset:192
.LBB0_337:
	s_and_b64 vcc, exec, s[12:13]
	s_cbranch_vccnz .LBB0_339
	v_ashrrev_i32_e32 v4, 31, v68
	v_mul_lo_u32 v6, s63, v68
	v_mul_lo_u32 v7, s62, v4
	v_mad_u64_u32 v[4:5], s[4:5], s62, v68, 0
	v_add3_u32 v5, v5, v7, v6
	v_lshl_add_u64 v[8:9], v[4:5], 1, v[222:223]
	v_cvt_pk_bf16_f32 v4, v132, v133
	v_cvt_pk_bf16_f32 v5, v134, v135
	v_cvt_pk_bf16_f32 v6, v136, v137
	v_cvt_pk_bf16_f32 v7, v138, v139
	s_nop 0
	v_permlane16_swap_b32_e32 v4, v6
	v_permlane16_swap_b32_e32 v5, v7
	ds_bpermute_b32 v236, v239, v8
	ds_bpermute_b32 v237, v239, v9
	ds_bpermute_b32 v240, v239, v4
	ds_bpermute_b32 v241, v239, v5
	ds_bpermute_b32 v242, v239, v6
	ds_bpermute_b32 v243, v239, v7
	s_waitcnt lgkmcnt(0)
	global_store_dwordx4 v[236:237], v[240:243], off
	s_nop 1
	v_cvt_pk_bf16_f32 v4, v140, v141
	v_cvt_pk_bf16_f32 v5, v142, v143
	v_cvt_pk_bf16_f32 v6, v144, v145
	v_cvt_pk_bf16_f32 v7, v146, v147
	s_nop 0
	v_permlane16_swap_b32_e32 v4, v6
	v_permlane16_swap_b32_e32 v5, v7
	ds_bpermute_b32 v244, v239, v4
	ds_bpermute_b32 v245, v239, v5
	ds_bpermute_b32 v246, v239, v6
	ds_bpermute_b32 v247, v239, v7
	s_waitcnt lgkmcnt(0)
	global_store_dwordx4 v[236:237], v[244:247], off offset:64

; DEVI f32x4 mfma16(bf16x8 a, bf16x8 b, f32x4 c) { return __builtin_amdgcn_mfma_f32_16x16x32_bf16(a, b, c, 0, 0, 0); }
; DEVI void mini_kloop(const bf16_t* __restrict__ arow, const bf16_t* __restrict__ b0, const bf16_t* __restrict__ b1, const int K, f32x4 (&acc)[2]) {
; #pragma unroll 8
;     for (int k0 = 0; k0 < K; k0 += 32) {
;         const bf16x8 af = *(const bf16x8*)(arow + k0), w0 = *(const bf16x8*)(b0 + k0), w1 = *(const bf16x8*)(b1 + k0);
;         acc[0] = mfma16(w0, af, acc[0]); acc[1] = mfma16(w1, af, acc[1]);
;     }
; }
; DEVI void mini_mix_tile(const Params& p, const int t) {
;     int tid = threadIdx.x; asm volatile("" : "+v"(tid));
;     const int lane = tid & 63, w = tid >> 6, l15 = lane & 15, g = lane >> 4;
;     const int tok = NTP + 64 * (t >> 4) + 16 * (w & 3) + l15, colw = 64 * (t & 15) + 32 * (w >> 2);
;     const bf16_t* OA = (const bf16_t*)(p.ws + W_OAB); const bf16_t* OB = OA + (size_t)NTOK * 512;
;     const bf16_t* WAT = (const bf16_t*)(p.ws + W_WABT); const bf16_t* WBT = WAT + 1024 * 512;
;     f32x4 aa[2] = {(f32x4){0.f, 0.f, 0.f, 0.f}, (f32x4){0.f, 0.f, 0.f, 0.f}}, ab[2] = {(f32x4){0.f, 0.f, 0.f, 0.f}, (f32x4){0.f, 0.f, 0.f, 0.f}};
;     mini_kloop(OA + (size_t)tok * 512 + 8 * g, WAT + (size_t)(colw + l15) * 512 + 8 * g, WAT + (size_t)(colw + 16 + l15) * 512 + 8 * g, 512, aa);
;     mini_kloop(OB + (size_t)tok * 512 + 8 * g, WBT + (size_t)(colw + l15) * 512 + 8 * g, WBT + (size_t)(colw + 16 + l15) * 512 + 8 * g, 512, ab);
.LBB0_995:
	v_mov_b32_e32 v8, 0
	v_mov_b32_e32 v9, 0
	v_mov_b32_e32 v10, 0
	v_mov_b32_e32 v11, 0
	v_mov_b32_e32 v12, 0
	v_mov_b32_e32 v13, 0
	v_mov_b32_e32 v14, 0
	v_mov_b32_e32 v15, 0
	v_lshl_add_u64 v[28:29], v[18:19], 0, v[16:17]
	v_lshl_add_u64 v[30:31], v[20:21], 0, v[16:17]
	v_lshl_add_u64 v[32:33], v[22:23], 0, v[16:17]
	v_add_co_u32_e32 v34, vcc, 0x1af48000, v28
	s_nop 1
	v_addc_co_u32_e32 v35, vcc, 0, v29, vcc
	v_add_co_u32_e32 v28, vcc, 0x18e48000, v28
	s_nop 1
	v_addc_co_u32_e32 v29, vcc, 0, v29, vcc
	v_add_co_u32_e32 v36, vcc, 0x5080000, v30
	s_nop 1
	v_addc_co_u32_e32 v37, vcc, 0, v31, vcc
	v_add_co_u32_e32 v30, vcc, 0x4f80000, v30
	s_nop 1
	v_addc_co_u32_e32 v31, vcc, 0, v31, vcc
	v_add_co_u32_e32 v38, vcc, 0x5080000, v32
	s_nop 1
	v_addc_co_u32_e32 v39, vcc, 0, v33, vcc
	v_add_co_u32_e32 v32, vcc, 0x4f80000, v32
	s_nop 1
	v_addc_co_u32_e32 v33, vcc, 0, v33, vcc
	global_load_dwordx4 v[64:67], v[28:29], off
	global_load_dwordx4 v[68:71], v[30:31], off
	global_load_dwordx4 v[72:75], v[32:33], off
	global_load_dwordx4 v[76:79], v[28:29], off offset:64
	global_load_dwordx4 v[80:83], v[30:31], off offset:64
	global_load_dwordx4 v[84:87], v[32:33], off offset:64
	global_load_dwordx4 v[88:91], v[28:29], off offset:128
	global_load_dwordx4 v[92:95], v[30:31], off offset:128
	global_load_dwordx4 v[96:99], v[32:33], off offset:128
	global_load_dwordx4 v[100:103], v[28:29], off offset:192
	global_load_dwordx4 v[104:107], v[30:31], off offset:192
	global_load_dwordx4 v[108:111], v[32:33], off offset:192
	global_load_dwordx4 v[112:115], v[28:29], off offset:256
	global_load_dwordx4 v[116:119], v[30:31], off offset:256
	global_load_dwordx4 v[120:123], v[32:33], off offset:256
	global_load_dwordx4 v[124:127], v[28:29], off offset:320
	global_load_dwordx4 v[128:131], v[30:31], off offset:320
	global_load_dwordx4 v[132:135], v[32:33], off offset:320
	global_load_dwordx4 v[136:139], v[28:29], off offset:384
	global_load_dwordx4 v[140:143], v[30:31], off offset:384
	global_load_dwordx4 v[144:147], v[32:33], off offset:384
	global_load_dwordx4 v[148:151], v[28:29], off offset:448
	global_load_dwordx4 v[152:155], v[30:31], off offset:448
	global_load_dwordx4 v[156:159], v[32:33], off offset:448
	s_waitcnt vmcnt(21)
	v_mfma_f32_16x16x32_bf16 v[4:7], v[68:71], v[64:67], v[4:7]
	v_mfma_f32_16x16x32_bf16 v[0:3], v[72:75], v[64:67], v[0:3]
	global_load_dwordx4 v[64:67], v[28:29], off offset:512
	global_load_dwordx4 v[68:71], v[30:31], off offset:512
	global_load_dwordx4 v[72:75], v[32:33], off offset:512
	s_waitcnt vmcnt(21)
	v_mfma_f32_16x16x32_bf16 v[4:7], v[80:83], v[76:79], v[4:7]
	v_mfma_f32_16x16x32_bf16 v[0:3], v[84:87], v[76:79], v[0:3]
	global_load_dwordx4 v[76:79], v[28:29], off offset:576
	global_load_dwordx4 v[80:83], v[30:31], off offset:576
	global_load_dwordx4 v[84:87], v[32:33], off offset:576
	s_waitcnt vmcnt(21)
	v_mfma_f32_16x16x32_bf16 v[4:7], v[92:95], v[88:91], v[4:7]
	v_mfma_f32_16x16x32_bf16 v[0:3], v[96:99], v[88:91], v[0:3]
	global_load_dwordx4 v[88:91], v[28:29], off offset:640
	global_load_dwordx4 v[92:95], v[30:31], off offset:640
	global_load_dwordx4 v[96:99], v[32:33], off offset:640
	s_waitcnt vmcnt(21)
	v_mfma_f32_16x16x32_bf16 v[4:7], v[104:107], v[100:103], v[4:7]
	v_mfma_f32_16x16x32_bf16 v[0:3], v[108:111], v[100:103], v[0:3]
	global_load_dwordx4 v[100:103], v[28:29], off offset:704
	global_load_dwordx4 v[104:107], v[30:31], off offset:704
	global_load_dwordx4 v[108:111], v[32:33], off offset:704
	s_waitcnt vmcnt(21)
	v_mfma_f32_16x16x32_bf16 v[4:7], v[116:119], v[112:115], v[4:7]
	v_mfma_f32_16x16x32_bf16 v[0:3], v[120:123], v[112:115], v[0:3]
	global_load_dwordx4 v[112:115], v[28:29], off offset:768
	global_load_dwordx4 v[116:119], v[30:31], off offset:768
	global_load_dwordx4 v[120:123], v[32:33], off offset:768
	s_waitcnt vmcnt(21)
	v_mfma_f32_16x16x32_bf16 v[4:7], v[128:131], v[124:127], v[4:7]
	v_mfma_f32_16x16x32_bf16 v[0:3], v[132:135], v[124:127], v[0:3]
	global_load_dwordx4 v[124:127], v[28:29], off offset:832
	global_load_dwordx4 v[128:131], v[30:31], off offset:832
	global_load_dwordx4 v[132:135], v[32:33], off offset:832
	s_waitcnt vmcnt(21)
	v_mfma_f32_16x16x32_bf16 v[4:7], v[140:143], v[136:139], v[4:7]
	v_mfma_f32_16x16x32_bf16 v[0:3], v[144:147], v[136:139], v[0:3]
	global_load_dwordx4 v[136:139], v[28:29], off offset:896
	global_load_dwordx4 v[140:143], v[30:31], off offset:896
	global_load_dwordx4 v[144:147], v[32:33], off offset:896
	s_waitcnt vmcnt(21)
	v_mfma_f32_16x16x32_bf16 v[4:7], v[152:155], v[148:151], v[4:7]
	v_mfma_f32_16x16x32_bf16 v[0:3], v[156:159], v[148:151], v[0:3]
	global_load_dwordx4 v[148:151], v[28:29], off offset:960
	global_load_dwordx4 v[152:155], v[30:31], off offset:960
	global_load_dwordx4 v[156:159], v[32:33], off offset:960
	s_waitcnt vmcnt(21)
	v_mfma_f32_16x16x32_bf16 v[4:7], v[68:71], v[64:67], v[4:7]
	v_mfma_f32_16x16x32_bf16 v[0:3], v[72:75], v[64:67], v[0:3]
	global_load_dwordx4 v[64:67], v[34:35], off
	global_load_dwordx4 v[68:71], v[36:37], off
	global_load_dwordx4 v[72:75], v[38:39], off
	s_waitcnt vmcnt(21)
	v_mfma_f32_16x16x32_bf16 v[4:7], v[80:83], v[76:79], v[4:7]
	v_mfma_f32_16x16x32_bf16 v[0:3], v[84:87], v[76:79], v[0:3]
	global_load_dwordx4 v[76:79], v[34:35], off offset:64
	global_load_dwordx4 v[80:83], v[36:37], off offset:64
	global_load_dwordx4 v[84:87], v[38:39], off offset:64
	s_waitcnt vmcnt(21)
	v_mfma_f32_16x16x32_bf16 v[4:7], v[92:95], v[88:91], v[4:7]
	v_mfma_f32_16x16x32_bf16 v[0:3], v[96:99], v[88:91], v[0:3]
	global_load_dwordx4 v[88:91], v[34:35], off offset:128
	global_load_dwordx4 v[92:95], v[36:37], off offset:128
	global_load_dwordx4 v[96:99], v[38:39], off offset:128
	s_waitcnt vmcnt(21)
; DEVI f32x4 mfma16(bf16x8 a, bf16x8 b, f32x4 c) { return __builtin_amdgcn_mfma_f32_16x16x32_bf16(a, b, c, 0, 0, 0); }
; DEVI void mini_kloop(const bf16_t* __restrict__ arow, const bf16_t* __restrict__ b0, const bf16_t* __restrict__ b1, const int K, f32x4 (&acc)[2]) {
; #pragma unroll 8
;     for (int k0 = 0; k0 < K; k0 += 32) {
;         const bf16x8 af = *(const bf16x8*)(arow + k0), w0 = *(const bf16x8*)(b0 + k0), w1 = *(const bf16x8*)(b1 + k0);
;         acc[0] = mfma16(w0, af, acc[0]); acc[1] = mfma16(w1, af, acc[1]);
;     }
; }
; DEVI void mini_mix_tile(const Params& p, const int t) {
;     int tid = threadIdx.x; asm volatile("" : "+v"(tid));
;     const int lane = tid & 63, w = tid >> 6, l15 = lane & 15, g = lane >> 4;
;     const int tok = NTP + 64 * (t >> 4) + 16 * (w & 3) + l15, colw = 64 * (t & 15) + 32 * (w >> 2);
;     const bf16_t* OA = (const bf16_t*)(p.ws + W_OAB); const bf16_t* OB = OA + (size_t)NTOK * 512;
;     const bf16_t* WAT = (const bf16_t*)(p.ws + W_WABT); const bf16_t* WBT = WAT + 1024 * 512;
;     f32x4 aa[2] = {(f32x4){0.f, 0.f, 0.f, 0.f}, (f32x4){0.f, 0.f, 0.f, 0.f}}, ab[2] = {(f32x4){0.f, 0.f, 0.f, 0.f}, (f32x4){0.f, 0.f, 0.f, 0.f}};
;     mini_kloop(OA + (size_t)tok * 512 + 8 * g, WAT + (size_t)(colw + l15) * 512 + 8 * g, WAT + (size_t)(colw + 16 + l15) * 512 + 8 * g, 512, aa);
;     mini_kloop(OB + (size_t)tok * 512 + 8 * g, WBT + (size_t)(colw + l15) * 512 + 8 * g, WBT + (size_t)(colw + 16 + l15) * 512 + 8 * g, 512, ab);
	v_mfma_f32_16x16x32_bf16 v[4:7], v[104:107], v[100:103], v[4:7]
	v_mfma_f32_16x16x32_bf16 v[0:3], v[108:111], v[100:103], v[0:3]
	global_load_dwordx4 v[100:103], v[34:35], off offset:192
	global_load_dwordx4 v[104:107], v[36:37], off offset:192
	global_load_dwordx4 v[108:111], v[38:39], off offset:192
	s_waitcnt vmcnt(21)
	v_mfma_f32_16x16x32_bf16 v[4:7], v[116:119], v[112:115], v[4:7]
	v_mfma_f32_16x16x32_bf16 v[0:3], v[120:123], v[112:115], v[0:3]
	global_load_dwordx4 v[112:115], v[34:35], off offset:256
	global_load_dwordx4 v[116:119], v[36:37], off offset:256
	global_load_dwordx4 v[120:123], v[38:39], off offset:256
	s_waitcnt vmcnt(21)
	v_mfma_f32_16x16x32_bf16 v[4:7], v[128:131], v[124:127], v[4:7]
	v_mfma_f32_16x16x32_bf16 v[0:3], v[132:135], v[124:127], v[0:3]
	global_load_dwordx4 v[124:127], v[34:35], off offset:320
	global_load_dwordx4 v[128:131], v[36:37], off offset:320
	global_load_dwordx4 v[132:135], v[38:39], off offset:320
	s_waitcnt vmcnt(21)
	v_mfma_f32_16x16x32_bf16 v[4:7], v[140:143], v[136:139], v[4:7]
	v_mfma_f32_16x16x32_bf16 v[0:3], v[144:147], v[136:139], v[0:3]
	global_load_dwordx4 v[136:139], v[34:35], off offset:384
	global_load_dwordx4 v[140:143], v[36:37], off offset:384
	global_load_dwordx4 v[144:147], v[38:39], off offset:384
	s_waitcnt vmcnt(21)
	v_mfma_f32_16x16x32_bf16 v[4:7], v[152:155], v[148:151], v[4:7]
	v_mfma_f32_16x16x32_bf16 v[0:3], v[156:159], v[148:151], v[0:3]
	global_load_dwordx4 v[148:151], v[34:35], off offset:448
	global_load_dwordx4 v[152:155], v[36:37], off offset:448
	global_load_dwordx4 v[156:159], v[38:39], off offset:448
	s_waitcnt vmcnt(21)
	v_mfma_f32_16x16x32_bf16 v[12:15], v[68:71], v[64:67], v[12:15]
	v_mfma_f32_16x16x32_bf16 v[8:11], v[72:75], v[64:67], v[8:11]
	global_load_dwordx4 v[64:67], v[34:35], off offset:512
	global_load_dwordx4 v[68:71], v[36:37], off offset:512
	global_load_dwordx4 v[72:75], v[38:39], off offset:512
	s_waitcnt vmcnt(21)
	v_mfma_f32_16x16x32_bf16 v[12:15], v[80:83], v[76:79], v[12:15]
	v_mfma_f32_16x16x32_bf16 v[8:11], v[84:87], v[76:79], v[8:11]
	global_load_dwordx4 v[76:79], v[34:35], off offset:576
	global_load_dwordx4 v[80:83], v[36:37], off offset:576
	global_load_dwordx4 v[84:87], v[38:39], off offset:576
	s_waitcnt vmcnt(21)
	v_mfma_f32_16x16x32_bf16 v[12:15], v[92:95], v[88:91], v[12:15]
	v_mfma_f32_16x16x32_bf16 v[8:11], v[96:99], v[88:91], v[8:11]
	global_load_dwordx4 v[88:91], v[34:35], off offset:640
	global_load_dwordx4 v[92:95], v[36:37], off offset:640
	global_load_dwordx4 v[96:99], v[38:39], off offset:640
	s_waitcnt vmcnt(21)
	v_mfma_f32_16x16x32_bf16 v[12:15], v[104:107], v[100:103], v[12:15]
	v_mfma_f32_16x16x32_bf16 v[8:11], v[108:111], v[100:103], v[8:11]
	global_load_dwordx4 v[100:103], v[34:35], off offset:704
	global_load_dwordx4 v[104:107], v[36:37], off offset:704
	global_load_dwordx4 v[108:111], v[38:39], off offset:704
	s_waitcnt vmcnt(21)
	v_mfma_f32_16x16x32_bf16 v[12:15], v[116:119], v[112:115], v[12:15]
	v_mfma_f32_16x16x32_bf16 v[8:11], v[120:123], v[112:115], v[8:11]
	global_load_dwordx4 v[112:115], v[34:35], off offset:768
	global_load_dwordx4 v[116:119], v[36:37], off offset:768
	global_load_dwordx4 v[120:123], v[38:39], off offset:768
	s_waitcnt vmcnt(21)
	v_mfma_f32_16x16x32_bf16 v[12:15], v[128:131], v[124:127], v[12:15]
	v_mfma_f32_16x16x32_bf16 v[8:11], v[132:135], v[124:127], v[8:11]
	global_load_dwordx4 v[124:127], v[34:35], off offset:832
	global_load_dwordx4 v[128:131], v[36:37], off offset:832
	global_load_dwordx4 v[132:135], v[38:39], off offset:832
	s_waitcnt vmcnt(21)
	v_mfma_f32_16x16x32_bf16 v[12:15], v[140:143], v[136:139], v[12:15]
	v_mfma_f32_16x16x32_bf16 v[8:11], v[144:147], v[136:139], v[8:11]
	global_load_dwordx4 v[136:139], v[34:35], off offset:896
	global_load_dwordx4 v[140:143], v[36:37], off offset:896
	global_load_dwordx4 v[144:147], v[38:39], off offset:896
	s_waitcnt vmcnt(21)
; DEVI unsigned pk_bf16(float lo, float hi) { const f32x2_t v = {lo, hi}; const bf16x2_t b = __builtin_convertvector(v, bf16x2_t); return __builtin_bit_cast(unsigned, b); }
; DEVI float bf_lo(unsigned u) { return __uint_as_float(u << 16); }
; DEVI float bf_hi(unsigned u) { return __uint_as_float(u & 0xffff0000u); }
; DEVI f32x4 mfma16(bf16x8 a, bf16x8 b, f32x4 c) { return __builtin_amdgcn_mfma_f32_16x16x32_bf16(a, b, c, 0, 0, 0); }
; DEVI void mini_kloop(const bf16_t* __restrict__ arow, const bf16_t* __restrict__ b0, const bf16_t* __restrict__ b1, const int K, f32x4 (&acc)[2]) {
;     ...
;         acc[0] = mfma16(w0, af, acc[0]); acc[1] = mfma16(w1, af, acc[1]);
;     }
; }
; DEVI void mini_mix_tile(const Params& p, const int t) {
;     int tid = threadIdx.x; asm volatile("" : "+v"(tid));
;     const int lane = tid & 63, w = tid >> 6, l15 = lane & 15, g = lane >> 4;
;     const int tok = NTP + 64 * (t >> 4) + 16 * (w & 3) + l15, colw = 64 * (t & 15) + 32 * (w >> 2);
;     const bf16_t* OA = (const bf16_t*)(p.ws + W_OAB); const bf16_t* OB = OA + (size_t)NTOK * 512;
;     const bf16_t* WAT = (const bf16_t*)(p.ws + W_WABT); const bf16_t* WBT = WAT + 1024 * 512;
;     f32x4 aa[2] = {(f32x4){0.f, 0.f, 0.f, 0.f}, (f32x4){0.f, 0.f, 0.f, 0.f}}, ab[2] = {(f32x4){0.f, 0.f, 0.f, 0.f}, (f32x4){0.f, 0.f, 0.f, 0.f}};
;     mini_kloop(OA + (size_t)tok * 512 + 8 * g, WAT + (size_t)(colw + l15) * 512 + 8 * g, WAT + (size_t)(colw + 16 + l15) * 512 + 8 * g, 512, aa);
;     mini_kloop(OB + (size_t)tok * 512 + 8 * g, WBT + (size_t)(colw + l15) * 512 + 8 * g, WBT + (size_t)(colw + 16 + l15) * 512 + 8 * g, 512, ab);
;     const bf16_t* G = (const bf16_t*)p.out; bf16_t* MX = (bf16_t*)(p.ws + W_XN);
; #pragma unroll
;     for (int tt = 0; tt < 2; ++tt) {
;         const int col = colw + 16 * tt + 4 * g;
;         const u32x2 ga = *(const u32x2*)(G + (size_t)tok * 2048 + col), gb = *(const u32x2*)(G + (size_t)tok * 2048 + 1024 + col);
;         f32x4 m;
;         m[0] = aa[tt][0] * bf_lo(ga.x) + ab[tt][0] * bf_lo(gb.x); m[1] = aa[tt][1] * bf_hi(ga.x) + ab[tt][1] * bf_hi(gb.x);
;         m[2] = aa[tt][2] * bf_lo(ga.y) + ab[tt][2] * bf_lo(gb.y); m[3] = aa[tt][3] * bf_hi(ga.y) + ab[tt][3] * bf_hi(gb.y);
;         u32x2 o; o.x = pk_bf16(m[0], m[1]); o.y = pk_bf16(m[2], m[3]);
;         *(u32x2*)(MX + (size_t)tok * 1024 + col) = o;
;     }
	v_mfma_f32_16x16x32_bf16 v[12:15], v[152:155], v[148:151], v[12:15]
	v_mfma_f32_16x16x32_bf16 v[8:11], v[156:159], v[148:151], v[8:11]
	global_load_dwordx4 v[148:151], v[34:35], off offset:960
	global_load_dwordx4 v[152:155], v[36:37], off offset:960
	global_load_dwordx4 v[156:159], v[38:39], off offset:960
	s_waitcnt vmcnt(21)
	v_mfma_f32_16x16x32_bf16 v[12:15], v[68:71], v[64:67], v[12:15]
	v_mfma_f32_16x16x32_bf16 v[8:11], v[72:75], v[64:67], v[8:11]
	s_waitcnt vmcnt(18)
	v_mfma_f32_16x16x32_bf16 v[12:15], v[80:83], v[76:79], v[12:15]
	v_mfma_f32_16x16x32_bf16 v[8:11], v[84:87], v[76:79], v[8:11]
	s_waitcnt vmcnt(15)
	v_mfma_f32_16x16x32_bf16 v[12:15], v[92:95], v[88:91], v[12:15]
	v_mfma_f32_16x16x32_bf16 v[8:11], v[96:99], v[88:91], v[8:11]
	s_waitcnt vmcnt(12)
	v_mfma_f32_16x16x32_bf16 v[12:15], v[104:107], v[100:103], v[12:15]
	v_mfma_f32_16x16x32_bf16 v[8:11], v[108:111], v[100:103], v[8:11]
	s_waitcnt vmcnt(9)
	v_mfma_f32_16x16x32_bf16 v[12:15], v[116:119], v[112:115], v[12:15]
	v_mfma_f32_16x16x32_bf16 v[8:11], v[120:123], v[112:115], v[8:11]
	s_waitcnt vmcnt(6)
	v_mfma_f32_16x16x32_bf16 v[12:15], v[128:131], v[124:127], v[12:15]
	v_mfma_f32_16x16x32_bf16 v[8:11], v[132:135], v[124:127], v[8:11]
	s_waitcnt vmcnt(3)
	v_mfma_f32_16x16x32_bf16 v[12:15], v[140:143], v[136:139], v[12:15]
	v_mfma_f32_16x16x32_bf16 v[8:11], v[144:147], v[136:139], v[8:11]
	s_waitcnt vmcnt(0)
	v_mfma_f32_16x16x32_bf16 v[12:15], v[152:155], v[148:151], v[12:15]
	v_mfma_f32_16x16x32_bf16 v[8:11], v[156:159], v[148:151], v[8:11]
	s_lshl_b32 s3, s7, 2
	s_andn2_b32 s3, s3, 63
	s_add_i32 s3, s3, 0x8000
	v_or3_b32 v18, v25, s3, v24
	s_lshl_b32 s3, s7, 6
	s_and_b32 s3, s3, 0x3c0
	v_and_b32_e32 v16, 3, v27
	v_add_u32_e32 v20, s3, v26
	v_ashrrev_i32_e32 v19, 31, v18
	v_lshl_or_b32 v20, v16, 2, v20
	v_readlane_b32 s12, v234, 24
	v_lshlrev_b64 v[22:23], 12, v[18:19]
	v_readlane_b32 s26, v234, 38
	v_readlane_b32 s27, v234, 39
	v_ashrrev_i32_e32 v21, 31, v20
	v_lshlrev_b64 v[20:21], 1, v[20:21]
	v_lshl_add_u64 v[22:23], s[26:27], 0, v[22:23]
	v_lshl_add_u64 v[22:23], v[22:23], 0, v[20:21]
	global_load_dwordx2 v[24:25], v[22:23], off
	global_load_dwordx2 v[26:27], v[22:23], off offset:2048
	v_lshlrev_b64 v[18:19], 11, v[18:19]
	v_lshl_add_u64 v[18:19], s[88:89], 0, v[18:19]
	v_lshl_add_u64 v[18:19], v[18:19], 0, v[20:21]
	s_add_i32 s7, s7, s97
	s_add_i32 s2, s2, s4
	s_add_i32 s5, s5, s6
	s_cmpk_gt_i32 s7, 0xff
	v_readlane_b32 s13, v234, 25
	v_readlane_b32 s14, v234, 26
	v_readlane_b32 s15, v234, 27
	v_readlane_b32 s16, v234, 28
	v_readlane_b32 s17, v234, 29
	v_readlane_b32 s18, v234, 30
	v_readlane_b32 s19, v234, 31
	v_readlane_b32 s20, v234, 32
	v_readlane_b32 s21, v234, 33
	v_readlane_b32 s22, v234, 34
	v_readlane_b32 s23, v234, 35
	v_readlane_b32 s24, v234, 36
	v_readlane_b32 s25, v234, 37
	s_waitcnt vmcnt(1)
	v_lshlrev_b32_e32 v20, 16, v24
	s_waitcnt vmcnt(0)
	v_lshlrev_b32_e32 v28, 16, v26
	v_and_b32_e32 v29, 0xffff0000, v26
	v_lshlrev_b32_e32 v26, 16, v27
	v_and_b32_e32 v27, 0xffff0000, v27
	v_and_b32_e32 v21, 0xffff0000, v24
	v_lshlrev_b32_e32 v24, 16, v25
	v_and_b32_e32 v25, 0xffff0000, v25
	v_pk_mul_f32 v[12:13], v[12:13], v[28:29]
	v_pk_mul_f32 v[14:15], v[14:15], v[26:27]
	v_pk_fma_f32 v[4:5], v[4:5], v[20:21], v[12:13]
	v_pk_fma_f32 v[6:7], v[6:7], v[24:25], v[14:15]
	v_cvt_pk_bf16_f32 v4, v4, v5
	v_cvt_pk_bf16_f32 v5, v6, v7
	global_store_dwordx2 v[18:19], v[4:5], off
	global_load_dwordx2 v[4:5], v[22:23], off offset:32
	s_nop 0
	global_load_dwordx2 v[6:7], v[22:23], off offset:2080
	s_waitcnt vmcnt(1)
	v_lshlrev_b32_e32 v12, 16, v4
	s_waitcnt vmcnt(0)
	v_lshlrev_b32_e32 v14, 16, v6
	v_and_b32_e32 v15, 0xffff0000, v6
	v_lshlrev_b32_e32 v6, 16, v7
	v_and_b32_e32 v7, 0xffff0000, v7
	v_and_b32_e32 v13, 0xffff0000, v4
	v_lshlrev_b32_e32 v4, 16, v5
	v_and_b32_e32 v5, 0xffff0000, v5
	v_pk_mul_f32 v[8:9], v[8:9], v[14:15]
	v_pk_mul_f32 v[6:7], v[10:11], v[6:7]
	v_pk_fma_f32 v[0:1], v[0:1], v[12:13], v[8:9]
	v_pk_fma_f32 v[2:3], v[2:3], v[4:5], v[6:7]
	v_cvt_pk_bf16_f32 v0, v0, v1
	v_cvt_pk_bf16_f32 v1, v2, v3
	global_store_dwordx2 v[18:19], v[0:1], off offset:32
	s_cbranch_scc0 .LBB0_994

; DEVI f32x4 mfma16(bf16x8 a, bf16x8 b, f32x4 c) { return __builtin_amdgcn_mfma_f32_16x16x32_bf16(a, b, c, 0, 0, 0); }
; DEVI void mini_kloop(const bf16_t* __restrict__ arow, const bf16_t* __restrict__ b0, const bf16_t* __restrict__ b1, const int K, f32x4 (&acc)[2]) {
; #pragma unroll 8
;     for (int k0 = 0; k0 < K; k0 += 32) {
;         const bf16x8 af = *(const bf16x8*)(arow + k0), w0 = *(const bf16x8*)(b0 + k0), w1 = *(const bf16x8*)(b1 + k0);
;         acc[0] = mfma16(w0, af, acc[0]); acc[1] = mfma16(w1, af, acc[1]);
;     }
; }
; DEVI void mini_y_tile(const Params& p, const int t) {
;     ...
;     mini_kloop(MX + (size_t)tok * 1024 + 8 * g, WOT + (size_t)(colw + l15) * 1024 + 8 * g, WOT + (size_t)(colw + 16 + l15) * 1024 + 8 * g, 1024, acc);
.LBB0_1208:
	v_lshl_add_u64 v[20:21], v[12:13], 0, v[8:9]
	v_lshl_add_u64 v[22:23], v[14:15], 0, v[8:9]
	v_lshl_add_u64 v[24:25], v[10:11], 0, v[8:9]
	v_add_co_u32_e32 v22, vcc, s9, v22
	s_nop 1
	v_addc_co_u32_e32 v23, vcc, 0, v23, vcc
	v_add_co_u32_e32 v24, vcc, s9, v24
	s_nop 1
	v_addc_co_u32_e32 v25, vcc, 0, v25, vcc
	global_load_dwordx4 v[64:67], v[20:21], off
	global_load_dwordx4 v[68:71], v[22:23], off
	global_load_dwordx4 v[72:75], v[24:25], off
	global_load_dwordx4 v[76:79], v[20:21], off offset:64
	global_load_dwordx4 v[80:83], v[22:23], off offset:64
	global_load_dwordx4 v[84:87], v[24:25], off offset:64
	global_load_dwordx4 v[88:91], v[20:21], off offset:128
	global_load_dwordx4 v[92:95], v[22:23], off offset:128
	global_load_dwordx4 v[96:99], v[24:25], off offset:128
	global_load_dwordx4 v[100:103], v[20:21], off offset:192
	global_load_dwordx4 v[104:107], v[22:23], off offset:192
	global_load_dwordx4 v[108:111], v[24:25], off offset:192
	global_load_dwordx4 v[112:115], v[20:21], off offset:256
	global_load_dwordx4 v[116:119], v[22:23], off offset:256
	global_load_dwordx4 v[120:123], v[24:25], off offset:256
	global_load_dwordx4 v[124:127], v[20:21], off offset:320
	global_load_dwordx4 v[128:131], v[22:23], off offset:320
	global_load_dwordx4 v[132:135], v[24:25], off offset:320
	global_load_dwordx4 v[136:139], v[20:21], off offset:384
	global_load_dwordx4 v[140:143], v[22:23], off offset:384
	global_load_dwordx4 v[144:147], v[24:25], off offset:384
	global_load_dwordx4 v[148:151], v[20:21], off offset:448
	global_load_dwordx4 v[152:155], v[22:23], off offset:448
	global_load_dwordx4 v[156:159], v[24:25], off offset:448
	s_waitcnt vmcnt(21)
	v_mfma_f32_16x16x32_bf16 v[4:7], v[68:71], v[64:67], v[4:7]
	v_mfma_f32_16x16x32_bf16 v[0:3], v[72:75], v[64:67], v[0:3]
	global_load_dwordx4 v[64:67], v[20:21], off offset:512
	global_load_dwordx4 v[68:71], v[22:23], off offset:512
	global_load_dwordx4 v[72:75], v[24:25], off offset:512
	s_waitcnt vmcnt(21)
	v_mfma_f32_16x16x32_bf16 v[4:7], v[80:83], v[76:79], v[4:7]
	v_mfma_f32_16x16x32_bf16 v[0:3], v[84:87], v[76:79], v[0:3]
	global_load_dwordx4 v[76:79], v[20:21], off offset:576
	global_load_dwordx4 v[80:83], v[22:23], off offset:576
	global_load_dwordx4 v[84:87], v[24:25], off offset:576
	s_waitcnt vmcnt(21)
	v_mfma_f32_16x16x32_bf16 v[4:7], v[92:95], v[88:91], v[4:7]
	v_mfma_f32_16x16x32_bf16 v[0:3], v[96:99], v[88:91], v[0:3]
	global_load_dwordx4 v[88:91], v[20:21], off offset:640
	global_load_dwordx4 v[92:95], v[22:23], off offset:640
	global_load_dwordx4 v[96:99], v[24:25], off offset:640
	s_waitcnt vmcnt(21)
	v_mfma_f32_16x16x32_bf16 v[4:7], v[104:107], v[100:103], v[4:7]
	v_mfma_f32_16x16x32_bf16 v[0:3], v[108:111], v[100:103], v[0:3]
	global_load_dwordx4 v[100:103], v[20:21], off offset:704
	global_load_dwordx4 v[104:107], v[22:23], off offset:704
	global_load_dwordx4 v[108:111], v[24:25], off offset:704
	s_waitcnt vmcnt(21)
	v_mfma_f32_16x16x32_bf16 v[4:7], v[116:119], v[112:115], v[4:7]
	v_mfma_f32_16x16x32_bf16 v[0:3], v[120:123], v[112:115], v[0:3]
	global_load_dwordx4 v[112:115], v[20:21], off offset:768
	global_load_dwordx4 v[116:119], v[22:23], off offset:768
	global_load_dwordx4 v[120:123], v[24:25], off offset:768
	s_waitcnt vmcnt(21)
	v_mfma_f32_16x16x32_bf16 v[4:7], v[128:131], v[124:127], v[4:7]
	v_mfma_f32_16x16x32_bf16 v[0:3], v[132:135], v[124:127], v[0:3]
	global_load_dwordx4 v[124:127], v[20:21], off offset:832
	global_load_dwordx4 v[128:131], v[22:23], off offset:832
	global_load_dwordx4 v[132:135], v[24:25], off offset:832
	s_waitcnt vmcnt(21)
	v_mfma_f32_16x16x32_bf16 v[4:7], v[140:143], v[136:139], v[4:7]
	v_mfma_f32_16x16x32_bf16 v[0:3], v[144:147], v[136:139], v[0:3]
	global_load_dwordx4 v[136:139], v[20:21], off offset:896
	global_load_dwordx4 v[140:143], v[22:23], off offset:896
	global_load_dwordx4 v[144:147], v[24:25], off offset:896
	s_waitcnt vmcnt(21)
	v_mfma_f32_16x16x32_bf16 v[4:7], v[152:155], v[148:151], v[4:7]
	v_mfma_f32_16x16x32_bf16 v[0:3], v[156:159], v[148:151], v[0:3]
	global_load_dwordx4 v[148:151], v[20:21], off offset:960
	global_load_dwordx4 v[152:155], v[22:23], off offset:960
	global_load_dwordx4 v[156:159], v[24:25], off offset:960
	s_waitcnt vmcnt(21)
	v_mfma_f32_16x16x32_bf16 v[4:7], v[68:71], v[64:67], v[4:7]
	v_mfma_f32_16x16x32_bf16 v[0:3], v[72:75], v[64:67], v[0:3]
	global_load_dwordx4 v[64:67], v[20:21], off offset:1024
	global_load_dwordx4 v[68:71], v[22:23], off offset:1024
	global_load_dwordx4 v[72:75], v[24:25], off offset:1024
	s_waitcnt vmcnt(21)
	v_mfma_f32_16x16x32_bf16 v[4:7], v[80:83], v[76:79], v[4:7]
	v_mfma_f32_16x16x32_bf16 v[0:3], v[84:87], v[76:79], v[0:3]
	global_load_dwordx4 v[76:79], v[20:21], off offset:1088
	global_load_dwordx4 v[80:83], v[22:23], off offset:1088
	global_load_dwordx4 v[84:87], v[24:25], off offset:1088
	s_waitcnt vmcnt(21)
	v_mfma_f32_16x16x32_bf16 v[4:7], v[92:95], v[88:91], v[4:7]
	v_mfma_f32_16x16x32_bf16 v[0:3], v[96:99], v[88:91], v[0:3]
	global_load_dwordx4 v[88:91], v[20:21], off offset:1152
	global_load_dwordx4 v[92:95], v[22:23], off offset:1152
	global_load_dwordx4 v[96:99], v[24:25], off offset:1152
	s_waitcnt vmcnt(21)
	v_mfma_f32_16x16x32_bf16 v[4:7], v[104:107], v[100:103], v[4:7]
	v_mfma_f32_16x16x32_bf16 v[0:3], v[108:111], v[100:103], v[0:3]
	global_load_dwordx4 v[100:103], v[20:21], off offset:1216
	global_load_dwordx4 v[104:107], v[22:23], off offset:1216
	global_load_dwordx4 v[108:111], v[24:25], off offset:1216
	s_waitcnt vmcnt(21)
; DEVI f32x4 mfma16(bf16x8 a, bf16x8 b, f32x4 c) { return __builtin_amdgcn_mfma_f32_16x16x32_bf16(a, b, c, 0, 0, 0); }
; DEVI void mini_kloop(const bf16_t* __restrict__ arow, const bf16_t* __restrict__ b0, const bf16_t* __restrict__ b1, const int K, f32x4 (&acc)[2]) {
; #pragma unroll 8
;     for (int k0 = 0; k0 < K; k0 += 32) {
;         const bf16x8 af = *(const bf16x8*)(arow + k0), w0 = *(const bf16x8*)(b0 + k0), w1 = *(const bf16x8*)(b1 + k0);
;         acc[0] = mfma16(w0, af, acc[0]); acc[1] = mfma16(w1, af, acc[1]);
;     }
; }
; DEVI void mini_y_tile(const Params& p, const int t) {
;     ...
;     mini_kloop(MX + (size_t)tok * 1024 + 8 * g, WOT + (size_t)(colw + l15) * 1024 + 8 * g, WOT + (size_t)(colw + 16 + l15) * 1024 + 8 * g, 1024, acc);
	v_mfma_f32_16x16x32_bf16 v[4:7], v[116:119], v[112:115], v[4:7]
	v_mfma_f32_16x16x32_bf16 v[0:3], v[120:123], v[112:115], v[0:3]
	global_load_dwordx4 v[112:115], v[20:21], off offset:1280
	global_load_dwordx4 v[116:119], v[22:23], off offset:1280
	global_load_dwordx4 v[120:123], v[24:25], off offset:1280
	s_waitcnt vmcnt(21)
	v_mfma_f32_16x16x32_bf16 v[4:7], v[128:131], v[124:127], v[4:7]
	v_mfma_f32_16x16x32_bf16 v[0:3], v[132:135], v[124:127], v[0:3]
	global_load_dwordx4 v[124:127], v[20:21], off offset:1344
	global_load_dwordx4 v[128:131], v[22:23], off offset:1344
	global_load_dwordx4 v[132:135], v[24:25], off offset:1344
	s_waitcnt vmcnt(21)
	v_mfma_f32_16x16x32_bf16 v[4:7], v[140:143], v[136:139], v[4:7]
	v_mfma_f32_16x16x32_bf16 v[0:3], v[144:147], v[136:139], v[0:3]
	global_load_dwordx4 v[136:139], v[20:21], off offset:1408
	global_load_dwordx4 v[140:143], v[22:23], off offset:1408
	global_load_dwordx4 v[144:147], v[24:25], off offset:1408
	s_waitcnt vmcnt(21)
	v_mfma_f32_16x16x32_bf16 v[4:7], v[152:155], v[148:151], v[4:7]
	v_mfma_f32_16x16x32_bf16 v[0:3], v[156:159], v[148:151], v[0:3]
	global_load_dwordx4 v[148:151], v[20:21], off offset:1472
	global_load_dwordx4 v[152:155], v[22:23], off offset:1472
	global_load_dwordx4 v[156:159], v[24:25], off offset:1472
	s_waitcnt vmcnt(21)
	v_mfma_f32_16x16x32_bf16 v[4:7], v[68:71], v[64:67], v[4:7]
	v_mfma_f32_16x16x32_bf16 v[0:3], v[72:75], v[64:67], v[0:3]
	global_load_dwordx4 v[64:67], v[20:21], off offset:1536
	global_load_dwordx4 v[68:71], v[22:23], off offset:1536
	global_load_dwordx4 v[72:75], v[24:25], off offset:1536
	s_waitcnt vmcnt(21)
	v_mfma_f32_16x16x32_bf16 v[4:7], v[80:83], v[76:79], v[4:7]
	v_mfma_f32_16x16x32_bf16 v[0:3], v[84:87], v[76:79], v[0:3]
	global_load_dwordx4 v[76:79], v[20:21], off offset:1600
	global_load_dwordx4 v[80:83], v[22:23], off offset:1600
	global_load_dwordx4 v[84:87], v[24:25], off offset:1600
	s_waitcnt vmcnt(21)
	v_mfma_f32_16x16x32_bf16 v[4:7], v[92:95], v[88:91], v[4:7]
	v_mfma_f32_16x16x32_bf16 v[0:3], v[96:99], v[88:91], v[0:3]
	global_load_dwordx4 v[88:91], v[20:21], off offset:1664
	global_load_dwordx4 v[92:95], v[22:23], off offset:1664
	global_load_dwordx4 v[96:99], v[24:25], off offset:1664
	s_waitcnt vmcnt(21)
	v_mfma_f32_16x16x32_bf16 v[4:7], v[104:107], v[100:103], v[4:7]
	v_mfma_f32_16x16x32_bf16 v[0:3], v[108:111], v[100:103], v[0:3]
	global_load_dwordx4 v[100:103], v[20:21], off offset:1728
	global_load_dwordx4 v[104:107], v[22:23], off offset:1728
	global_load_dwordx4 v[108:111], v[24:25], off offset:1728
	s_waitcnt vmcnt(21)
	v_mfma_f32_16x16x32_bf16 v[4:7], v[116:119], v[112:115], v[4:7]
	v_mfma_f32_16x16x32_bf16 v[0:3], v[120:123], v[112:115], v[0:3]
	global_load_dwordx4 v[112:115], v[20:21], off offset:1792
	global_load_dwordx4 v[116:119], v[22:23], off offset:1792
	global_load_dwordx4 v[120:123], v[24:25], off offset:1792
	s_waitcnt vmcnt(21)
	v_mfma_f32_16x16x32_bf16 v[4:7], v[128:131], v[124:127], v[4:7]
	v_mfma_f32_16x16x32_bf16 v[0:3], v[132:135], v[124:127], v[0:3]
	global_load_dwordx4 v[124:127], v[20:21], off offset:1856
	global_load_dwordx4 v[128:131], v[22:23], off offset:1856
	global_load_dwordx4 v[132:135], v[24:25], off offset:1856
	s_waitcnt vmcnt(21)
	v_mfma_f32_16x16x32_bf16 v[4:7], v[140:143], v[136:139], v[4:7]
	v_mfma_f32_16x16x32_bf16 v[0:3], v[144:147], v[136:139], v[0:3]
	global_load_dwordx4 v[136:139], v[20:21], off offset:1920
	global_load_dwordx4 v[140:143], v[22:23], off offset:1920
	global_load_dwordx4 v[144:147], v[24:25], off offset:1920
	s_waitcnt vmcnt(21)
; DEVI void mini_y_tile(const Params& p, const int t) {
;     ...
;     mini_kloop(MX + (size_t)tok * 1024 + 8 * g, WOT + (size_t)(colw + l15) * 1024 + 8 * g, WOT + (size_t)(colw + 16 + l15) * 1024 + 8 * g, 1024, acc);
;     const float* xr = p.x_s + (size_t)(tok - NTP) * 1024;
; #pragma unroll
;     for (int tt = 0; tt < 2; ++tt) {
;         const int col = colw + 16 * tt + 4 * g;
;         const f32x4 xv = *(const f32x4*)(xr + col);
;         *(f32x4*)(p.out + (size_t)tok * 1024 + col) = xv + acc[tt];
;     }
	v_mfma_f32_16x16x32_bf16 v[4:7], v[152:155], v[148:151], v[4:7]
	v_mfma_f32_16x16x32_bf16 v[0:3], v[156:159], v[148:151], v[0:3]
	global_load_dwordx4 v[148:151], v[20:21], off offset:1984
	global_load_dwordx4 v[152:155], v[22:23], off offset:1984
	global_load_dwordx4 v[156:159], v[24:25], off offset:1984
	s_waitcnt vmcnt(21)
	v_mfma_f32_16x16x32_bf16 v[4:7], v[68:71], v[64:67], v[4:7]
	v_mfma_f32_16x16x32_bf16 v[0:3], v[72:75], v[64:67], v[0:3]
	s_waitcnt vmcnt(18)
	v_mfma_f32_16x16x32_bf16 v[4:7], v[80:83], v[76:79], v[4:7]
	v_mfma_f32_16x16x32_bf16 v[0:3], v[84:87], v[76:79], v[0:3]
	s_waitcnt vmcnt(15)
	v_mfma_f32_16x16x32_bf16 v[4:7], v[92:95], v[88:91], v[4:7]
	v_mfma_f32_16x16x32_bf16 v[0:3], v[96:99], v[88:91], v[0:3]
	s_waitcnt vmcnt(12)
	v_mfma_f32_16x16x32_bf16 v[4:7], v[104:107], v[100:103], v[4:7]
	v_mfma_f32_16x16x32_bf16 v[0:3], v[108:111], v[100:103], v[0:3]
	s_waitcnt vmcnt(9)
	v_mfma_f32_16x16x32_bf16 v[4:7], v[116:119], v[112:115], v[4:7]
	v_mfma_f32_16x16x32_bf16 v[0:3], v[120:123], v[112:115], v[0:3]
	s_waitcnt vmcnt(6)
	v_mfma_f32_16x16x32_bf16 v[4:7], v[128:131], v[124:127], v[4:7]
	v_mfma_f32_16x16x32_bf16 v[0:3], v[132:135], v[124:127], v[0:3]
	s_waitcnt vmcnt(3)
	v_mfma_f32_16x16x32_bf16 v[4:7], v[140:143], v[136:139], v[4:7]
	v_mfma_f32_16x16x32_bf16 v[0:3], v[144:147], v[136:139], v[0:3]
	s_waitcnt vmcnt(0)
	v_mfma_f32_16x16x32_bf16 v[4:7], v[152:155], v[148:151], v[4:7]
	v_mfma_f32_16x16x32_bf16 v[0:3], v[156:159], v[148:151], v[0:3]
	s_lshl_b32 s3, s11, 2
	s_andn2_b32 s3, s3, 63
	s_add_i32 s3, s3, 0x8000
	v_or3_b32 v10, v17, s3, v16
	s_lshl_b32 s3, s11, 6
	s_and_b32 s3, s3, 0x3c0
	v_and_b32_e32 v8, 3, v19
	v_add_u32_e32 v12, s3, v18
	v_ashrrev_i32_e32 v11, 31, v10
	v_readlane_b32 s12, v234, 2
	v_lshl_or_b32 v12, v8, 2, v12
	v_lshlrev_b64 v[14:15], 12, v[10:11]
	v_readlane_b32 s14, v234, 4
	v_readlane_b32 s15, v234, 5
	v_ashrrev_i32_e32 v13, 31, v12
	v_lshlrev_b64 v[16:17], 2, v[12:13]
	v_lshl_add_u64 v[10:11], s[14:15], 0, v[14:15]
	v_lshl_add_u64 v[18:19], v[10:11], 0, v[16:17]
	v_add_co_u32_e32 v10, vcc, s10, v18
	v_readlane_b32 s13, v234, 3
	s_nop 0
	v_addc_co_u32_e32 v11, vcc, -1, v19, vcc
	global_load_dwordx4 v[10:13], v[10:11], off
	v_readlane_b32 s16, v234, 6
	v_readlane_b32 s17, v234, 7
	v_readlane_b32 s18, v234, 8
	v_readlane_b32 s19, v234, 9
	v_readlane_b32 s20, v234, 10
	v_readlane_b32 s21, v234, 11
	v_readlane_b32 s22, v234, 12
	v_readlane_b32 s23, v234, 13
	v_readlane_b32 s24, v234, 14
	v_readlane_b32 s25, v234, 15
	v_readlane_b32 s26, v234, 16
	v_readlane_b32 s27, v234, 17
	v_readlane_b32 s12, v234, 24
	v_readlane_b32 s26, v234, 38
	v_readlane_b32 s27, v234, 39
	s_add_i32 s11, s11, s97
	s_add_i32 s2, s2, s6
	v_lshl_add_u64 v[14:15], s[26:27], 0, v[14:15]
	v_lshl_add_u64 v[14:15], v[14:15], 0, v[16:17]
	v_lshl_add_u64 v[16:17], v[18:19], 0, s[4:5]
	s_add_i32 s7, s7, s8
	s_cmpk_gt_i32 s11, 0xff
	v_readlane_b32 s13, v234, 25
	v_readlane_b32 s14, v234, 26
	v_readlane_b32 s15, v234, 27
	v_readlane_b32 s16, v234, 28
	v_readlane_b32 s17, v234, 29
	v_readlane_b32 s18, v234, 30
	v_readlane_b32 s19, v234, 31
	v_readlane_b32 s20, v234, 32
	v_readlane_b32 s21, v234, 33
	v_readlane_b32 s22, v234, 34
	v_readlane_b32 s23, v234, 35
	v_readlane_b32 s24, v234, 36
	v_readlane_b32 s25, v234, 37
	s_waitcnt vmcnt(0)
	v_pk_add_f32 v[6:7], v[6:7], v[12:13]
	v_pk_add_f32 v[4:5], v[4:5], v[10:11]
	global_store_dwordx4 v[14:15], v[4:7], off
	global_load_dwordx4 v[4:7], v[16:17], off offset:64
	s_waitcnt vmcnt(0)
	v_pk_add_f32 v[2:3], v[2:3], v[6:7]
	v_pk_add_f32 v[0:1], v[0:1], v[4:5]
	global_store_dwordx4 v[14:15], v[0:3], off offset:64
	s_cbranch_scc0 .LBB0_1207

; template <int LO, int HI>
; __global__ void __launch_bounds__(NTHREADS) fwd_kernel(const Params p) {
	.amdhsa_kernel _Z10fwd_kernelILi0ELi5EEv6Params
		.amdhsa_group_segment_fixed_size 0
		.amdhsa_private_segment_fixed_size 0
		.amdhsa_kernarg_size 392
		.amdhsa_user_sgpr_count 2
		.amdhsa_user_sgpr_dispatch_ptr 0
		.amdhsa_user_sgpr_queue_ptr 0
		.amdhsa_user_sgpr_kernarg_segment_ptr 1
		.amdhsa_user_sgpr_dispatch_id 0
		.amdhsa_user_sgpr_kernarg_preload_length 0
		.amdhsa_user_sgpr_kernarg_preload_offset 0
		.amdhsa_user_sgpr_private_segment_size 0
		.amdhsa_uses_dynamic_stack 0
		.amdhsa_enable_private_segment 0
		.amdhsa_system_sgpr_workgroup_id_x 1
		.amdhsa_system_sgpr_workgroup_id_y 0
		.amdhsa_system_sgpr_workgroup_id_z 0
		.amdhsa_system_sgpr_workgroup_info 0
		.amdhsa_system_vgpr_workitem_id 2
		.amdhsa_next_free_vgpr 256
		.amdhsa_next_free_sgpr 98
		.amdhsa_accum_offset 256
		.amdhsa_reserve_vcc 1
		.amdhsa_float_round_mode_32 0
		.amdhsa_float_round_mode_16_64 0
		.amdhsa_float_denorm_mode_32 3
		.amdhsa_float_denorm_mode_16_64 3
		.amdhsa_dx10_clamp 1
		.amdhsa_ieee_mode 1
		.amdhsa_fp16_overflow 0
		.amdhsa_tg_split 0
		.amdhsa_exception_fp_ieee_invalid_op 0
		.amdhsa_exception_fp_denorm_src 0
		.amdhsa_exception_fp_ieee_div_zero 0
		.amdhsa_exception_fp_ieee_overflow 0
		.amdhsa_exception_fp_ieee_underflow 0
		.amdhsa_exception_fp_ieee_inexact 0
		.amdhsa_exception_int_div_zero 0
	.end_amdhsa_kernel

; template <int LO, int HI>
; __global__ void __launch_bounds__(NTHREADS) fwd_kernel(const Params p) {
amdhsa.kernels:
  - .agpr_count:     0
    .args:
      - .offset:         0
        .size:           136
        .value_kind:     by_value
      - .offset:         136
        .size:           4
        .value_kind:     hidden_block_count_x
      - .offset:         140
        .size:           4
        .value_kind:     hidden_block_count_y
      - .offset:         144
        .size:           4
        .value_kind:     hidden_block_count_z
      - .offset:         148
        .size:           2
        .value_kind:     hidden_group_size_x
      - .offset:         150
        .size:           2
        .value_kind:     hidden_group_size_y
      - .offset:         152
        .size:           2
        .value_kind:     hidden_group_size_z
      - .offset:         154
        .size:           2
        .value_kind:     hidden_remainder_x
      - .offset:         156
        .size:           2
        .value_kind:     hidden_remainder_y
      - .offset:         158
        .size:           2
        .value_kind:     hidden_remainder_z
      - .offset:         176
        .size:           8
        .value_kind:     hidden_global_offset_x
      - .offset:         184
        .size:           8
        .value_kind:     hidden_global_offset_y
      - .offset:         192
        .size:           8
        .value_kind:     hidden_global_offset_z
      - .offset:         200
        .size:           2
        .value_kind:     hidden_grid_dims
      - .offset:         224
        .size:           8
        .value_kind:     hidden_multigrid_sync_arg
      - .offset:         256
        .size:           4
        .value_kind:     hidden_dynamic_lds_size
    .group_segment_fixed_size: 0
    .kernarg_segment_align: 8
    .kernarg_segment_size: 392
    .language:       OpenCL C
    .language_version:
      - 2
      - 0
    .max_flat_workgroup_size: 512
    .name:           _Z10fwd_kernelILi0ELi5EEv6Params
    .private_segment_fixed_size: 0
    .sgpr_count:     104
    .sgpr_spill_count: 67
    .symbol:         _Z10fwd_kernelILi0ELi5EEv6Params.kd
    .uniform_work_group_size: 1
    .uses_dynamic_stack: false
    .vgpr_count:     256
    .vgpr_spill_count: 0
    .wavefront_size: 64
